# per-unit de-stagger in w1/w_in: leading wave group waits one barrier before its epilogue, trailing group one before K-loop re-entry, so both groups' epilogues run concurrently
# baseline (speedup 1.0000x reference)
; #define PG8_STAGE(bufoff, gbase, voff) do { _Pragma("unroll") for (int _i = 0; _i < 2; ++_i) \
;         __builtin_amdgcn_global_load_lds((const unsigned*)((const char*)(gbase) + (voff)[_i]), (LAS unsigned*)(lds + (bufoff) + ldsw + _i * 8192), 16, 0, 0); } while (0)
; #define PG8_WAIT_V(n) asm volatile("s_waitcnt vmcnt(" #n ")" ::: "memory")
; #define PG8_BAR __builtin_amdgcn_s_barrier()
; template <class Epi, class Sched>
; __device__ __forceinline__ void gemm_phase(LAS unsigned char* lds, const Gemm g, const Sched& S, const Epi& E) {
;     ...
;     const char* cA = (const char*)g.A + (size_t)cur.pm * tstep + (size_t)cur.ks * sstep; const char* cB = (const char*)g.Bt + (size_t)cur.pn * tstep + (size_t)cur.ks * sstep;
;     PG8_STAGE(PG8_SB(0, 0), cB, voffB); PG8_STAGE(PG8_SA(0, 0), cA, voffA); PG8_STAGE(PG8_SB(0, 1), cB + hstep, voffB); PG8_STAGE(PG8_SA(0, 1), cA + hstep, voffA);
;     if (wr == 1) PG8_BAR;
;     PG8_WAIT_V(4); PG8_BAR;
;     PG8_STAGE(PG8_SB(1, 0), cB + kstep, voffB); PG8_STAGE(PG8_SA(1, 0), cA + kstep, voffA); PG8_STAGE(PG8_SB(1, 1), cB + hstep + kstep, voffB);
;     PG8_WAIT_V(6); PG8_BAR;
;     for (;;) {
;         const bool has_next = S.next(ui + 1, nxt);
;         const char* nA = has_next ? (const char*)g.A + (size_t)nxt.pm * tstep + (size_t)nxt.ks * sstep : cA; const char* nB = has_next ? (const char*)g.Bt + (size_t)nxt.pn * tstep + (size_t)nxt.ks * sstep : cB;
;     ...
; #pragma unroll
;         for (int a = 0; a < 2; ++a)
; #pragma unroll
;             for (int b = 0; b < 2; ++b)
; #pragma unroll
;                 for (int m = 0; m < 4; ++m)
; #pragma unroll
;                     for (int n = 0; n < 2; ++n) acc[a][b][m][n] = (f32x4){0.f, 0.f, 0.f, 0.f};
;         cur = nxt; cA = nA; cB = nB; ++ui;
.LBB0_72:
	s_ashr_i32 s29, s28, 31
	v_mov_b64_e32 v[2:3], s[30:31]
	s_lshl_b64 s[38:39], s[28:29], 20
	v_cmp_lt_i64_e32 vcc, s[42:43], v[2:3]
	s_add_u32 s42, s10, s38
	s_addc_u32 s43, s11, s39
	s_and_b64 s[38:39], vcc, exec
	s_cselect_b32 s29, s43, s49
	s_cselect_b32 s69, s42, s48
	s_ashr_i32 s27, s26, 31
	s_lshl_b64 s[38:39], s[26:27], 20
	s_add_u32 s44, s53, s38
	s_addc_u32 s45, s54, s39
	s_and_b64 s[38:39], vcc, exec
	s_cselect_b32 s27, s45, s47
	s_cselect_b32 s70, s44, s46
	s_add_u32 s71, s46, 0x100
	s_addc_u32 s72, s47, 0
	s_add_u32 s46, s48, 0x80080
	v_mov_b32_e32 v2, 0
	s_addc_u32 s47, s49, 0
	s_mov_b32 s73, -2
	v_mov_b32_e32 v3, v2
	v_mov_b32_e32 v4, v2
	v_mov_b32_e32 v5, v2
	v_mov_b32_e32 v6, v2
	v_mov_b32_e32 v7, v2
	v_mov_b32_e32 v8, v2
	v_mov_b32_e32 v9, v2
	v_mov_b32_e32 v18, v2
	v_mov_b32_e32 v19, v2
	v_mov_b32_e32 v20, v2
	v_mov_b32_e32 v21, v2
	v_mov_b32_e32 v22, v2
	v_mov_b32_e32 v23, v2
	v_mov_b32_e32 v24, v2
	v_mov_b32_e32 v25, v2
	v_mov_b32_e32 v34, v2
	v_mov_b32_e32 v35, v2
	v_mov_b32_e32 v36, v2
	v_mov_b32_e32 v37, v2
	v_mov_b32_e32 v38, v2
	v_mov_b32_e32 v39, v2
	v_mov_b32_e32 v40, v2
	v_mov_b32_e32 v41, v2
	v_mov_b32_e32 v50, v2
	v_mov_b32_e32 v51, v2
	v_mov_b32_e32 v52, v2
	v_mov_b32_e32 v53, v2
	v_mov_b32_e32 v54, v2
	v_mov_b32_e32 v55, v2
	v_mov_b32_e32 v56, v2
	v_mov_b32_e32 v57, v2
	v_mov_b32_e32 v10, v2
	v_mov_b32_e32 v11, v2
	v_mov_b32_e32 v12, v2
	v_mov_b32_e32 v13, v2
	v_mov_b32_e32 v14, v2
	v_mov_b32_e32 v15, v2
	v_mov_b32_e32 v16, v2
	v_mov_b32_e32 v17, v2
	v_mov_b32_e32 v26, v2
	v_mov_b32_e32 v27, v2
	v_mov_b32_e32 v28, v2
	v_mov_b32_e32 v29, v2
	v_mov_b32_e32 v30, v2
	v_mov_b32_e32 v31, v2
	v_mov_b32_e32 v32, v2
	v_mov_b32_e32 v33, v2
	v_mov_b32_e32 v42, v2
	v_mov_b32_e32 v43, v2
	v_mov_b32_e32 v44, v2
	v_mov_b32_e32 v45, v2
	v_mov_b32_e32 v46, v2
	v_mov_b32_e32 v47, v2
	v_mov_b32_e32 v48, v2
	v_mov_b32_e32 v49, v2
	v_mov_b32_e32 v58, v2
	v_mov_b32_e32 v59, v2
	v_mov_b32_e32 v60, v2
	v_mov_b32_e32 v61, v2
	v_mov_b32_e32 v62, v2
	v_mov_b32_e32 v63, v2
	v_mov_b32_e32 v64, v2
	v_mov_b32_e32 v65, v2
	v_mov_b32_e32 v66, v2
	v_mov_b32_e32 v67, v2
	v_mov_b32_e32 v68, v2
	v_mov_b32_e32 v69, v2
	v_mov_b32_e32 v70, v2
	v_mov_b32_e32 v71, v2
	v_mov_b32_e32 v72, v2
	v_mov_b32_e32 v73, v2
	v_mov_b32_e32 v82, v2
	v_mov_b32_e32 v83, v2
	v_mov_b32_e32 v84, v2
	v_mov_b32_e32 v85, v2
	v_mov_b32_e32 v86, v2
	v_mov_b32_e32 v87, v2
	v_mov_b32_e32 v88, v2
	v_mov_b32_e32 v89, v2
	v_mov_b32_e32 v98, v2
	v_mov_b32_e32 v99, v2
	v_mov_b32_e32 v100, v2
	v_mov_b32_e32 v101, v2
	v_mov_b32_e32 v102, v2
	v_mov_b32_e32 v103, v2
	v_mov_b32_e32 v104, v2
	v_mov_b32_e32 v105, v2
	v_mov_b32_e32 v114, v2
	v_mov_b32_e32 v115, v2
	v_mov_b32_e32 v116, v2
	v_mov_b32_e32 v117, v2
	v_mov_b32_e32 v118, v2
	v_mov_b32_e32 v119, v2
	v_mov_b32_e32 v120, v2
	v_mov_b32_e32 v121, v2
	v_mov_b32_e32 v74, v2
	v_mov_b32_e32 v75, v2
	v_mov_b32_e32 v76, v2
	v_mov_b32_e32 v77, v2
	v_mov_b32_e32 v78, v2
	v_mov_b32_e32 v79, v2
	v_mov_b32_e32 v80, v2
	v_mov_b32_e32 v81, v2
	v_mov_b32_e32 v90, v2
	v_mov_b32_e32 v91, v2
	v_mov_b32_e32 v92, v2
	v_mov_b32_e32 v93, v2
	v_mov_b32_e32 v94, v2
	v_mov_b32_e32 v95, v2
	v_mov_b32_e32 v96, v2
	v_mov_b32_e32 v97, v2
	v_mov_b32_e32 v106, v2
	v_mov_b32_e32 v107, v2
	v_mov_b32_e32 v108, v2
	v_mov_b32_e32 v109, v2
	v_mov_b32_e32 v110, v2
	v_mov_b32_e32 v111, v2
	v_mov_b32_e32 v112, v2
	v_mov_b32_e32 v113, v2
	v_mov_b32_e32 v122, v2
	v_mov_b32_e32 v123, v2
	v_mov_b32_e32 v124, v2
	v_mov_b32_e32 v125, v2
	v_mov_b32_e32 v126, v2
	v_mov_b32_e32 v127, v2
	v_mov_b32_e32 v128, v2
	v_mov_b32_e32 v129, v2
	s_cmpk_gt_u32 s52, 0xff
	s_cbranch_scc0 .Ldsx1_73
	s_cmp_eq_u32 s67, 1
	s_cbranch_scc1 .Ldsx1_73
	s_barrier
.Ldsx1_73:
.LBB0_73:
	s_add_u32 s38, s46, 0xfff80080
	s_addc_u32 s39, s47, -1
	s_cmp_eq_u32 s73, 28
	s_cselect_b32 s51, s29, s39
	s_cselect_b32 s50, s69, s38
	s_cselect_b32 s49, s27, s72
	s_cselect_b32 s48, s70, s71
	s_add_i32 m0, s9, 0xc000
	s_nop 0
	global_load_lds_dwordx4 v138, s[46:47]
	s_add_i32 m0, s9, 0xe000
	s_nop 0
	global_load_lds_dwordx4 v136, s[46:47]
	s_add_i32 s74, 0, 0x10000
	ds_read_b128 v[146:149], v226
	ds_read_b128 v[150:153], v226 offset:1024
	ds_read_b128 v[154:157], v226 offset:2048
	ds_read_b128 v[160:163], v226 offset:3072
	ds_read_b128 v[164:167], v145
	ds_read_b128 v[168:171], v145 offset:1024
	ds_read_b128 v[172:175], v145 offset:2048
	ds_read_b128 v[176:179], v145 offset:3072
	ds_read_b128 v[180:183], v145 offset:4096
	ds_read_b128 v[184:187], v145 offset:5120
	ds_read_b128 v[188:191], v145 offset:6144
	ds_read_b128 v[192:195], v145 offset:7168
	s_add_i32 s75, 0, 0x14000
	ds_read_b128 v[196:199], v226 offset:16384
	ds_read_b128 v[200:203], v226 offset:17408
	ds_read_b128 v[204:207], v226 offset:18432
	ds_read_b128 v[210:213], v226 offset:19456
	s_waitcnt lgkmcnt(4)
	s_barrier
; #define PG8_STAGE(bufoff, gbase, voff) do { _Pragma("unroll") for (int _i = 0; _i < 2; ++_i) \
;         __builtin_amdgcn_global_load_lds((const unsigned*)((const char*)(gbase) + (voff)[_i]), (LAS unsigned*)(lds + (bufoff) + ldsw + _i * 8192), 16, 0, 0); } while (0)
; #define PG8_LDA(dst, b, h) do { _Pragma("unroll") for (int m = 0; m < 4; ++m) _Pragma("unroll") for (int k = 0; k < 2; ++k) dst[m][k] = *(const LAS bf16x8*)(lds + PG8_SA(b, h) + aoff + m * 2048 + k * 1024); } while (0)
; #define PG8_LDB(dst, b, h) do { _Pragma("unroll") for (int n = 0; n < 2; ++n) _Pragma("unroll") for (int k = 0; k < 2; ++k) dst[n][k] = *(const LAS bf16x8*)(lds + PG8_SB(b, h) + boff + n * 2048 + k * 1024); } while (0)
; #define PG8_MMA(ai, bj, At, Bt) do { __builtin_amdgcn_s_setprio(1); _Pragma("unroll") for (int m = 0; m < 4; ++m) _Pragma("unroll") for (int n = 0; n < 2; ++n) _Pragma("unroll") for (int k = 0; k < 2; ++k) \
;         acc[ai][bj][m][n] = __builtin_amdgcn_mfma_f32_16x16x32_bf16(Bt[n][k], At[m][k], acc[ai][bj][m][n], 0, 0, 0); __builtin_amdgcn_s_setprio(0); } while (0)
; #define PG8_WAIT_V(n) asm volatile("s_waitcnt vmcnt(" #n ")" ::: "memory")
; #define PG8_WAIT_L(n) asm volatile("s_waitcnt lgkmcnt(" #n ")" ::: "memory")
; #define PG8_BAR __builtin_amdgcn_s_barrier()
; #define PG8_SCHED __builtin_amdgcn_sched_barrier(0)
; template <class Epi, class Sched>
; __device__ __forceinline__ void gemm_phase(LAS unsigned char* lds, const Gemm g, const Sched& S, const Epi& E) {
;     ...
;             PG8_WAIT_L(8); PG8_BAR; PG8_WAIT_L(0); PG8_MMA(0, 0, At, B0); PG8_BAR; PG8_SCHED;
;             PG8_LDB(B1, 0, 1); PG8_STAGE(PG8_SB(0, 0), b2, voffB);
;             PG8_BAR; PG8_WAIT_L(0); PG8_MMA(0, 1, At, B1); PG8_BAR;
;             PG8_LDA(At, 0, 1); PG8_STAGE(PG8_SA(0, 0), a2, voffA);
;             PG8_BAR; PG8_WAIT_L(0); PG8_MMA(1, 0, At, B0); PG8_BAR; PG8_SCHED;
;             PG8_STAGE(PG8_SB(0, 1), b2 + hstep, voffB);
;             PG8_WAIT_V(6); PG8_BAR; PG8_MMA(1, 1, At, B1); PG8_BAR;
;             PG8_LDB(B0, 1, 0); PG8_SCHED; PG8_LDA(At, 1, 0); PG8_STAGE(PG8_SA(0, 1), a2 + hstep, voffA);
;             PG8_WAIT_L(8); PG8_BAR; PG8_WAIT_L(0); PG8_MMA(0, 0, At, B0); PG8_BAR; PG8_SCHED;
	s_waitcnt lgkmcnt(0)
	v_mfma_f32_16x16x32_bf16 v[126:129], v[146:149], v[164:167], v[126:129]
	v_mfma_f32_16x16x32_bf16 v[122:125], v[154:157], v[164:167], v[122:125]
	v_mfma_f32_16x16x32_bf16 v[110:113], v[146:149], v[172:175], v[110:113]
	v_mfma_f32_16x16x32_bf16 v[106:109], v[154:157], v[172:175], v[106:109]
	v_mfma_f32_16x16x32_bf16 v[94:97], v[146:149], v[180:183], v[94:97]
	v_mfma_f32_16x16x32_bf16 v[90:93], v[154:157], v[180:183], v[90:93]
	v_mfma_f32_16x16x32_bf16 v[78:81], v[146:149], v[188:191], v[78:81]
	v_mfma_f32_16x16x32_bf16 v[74:77], v[154:157], v[188:191], v[74:77]
	v_mfma_f32_16x16x32_bf16 v[126:129], v[150:153], v[168:171], v[126:129]
	v_mfma_f32_16x16x32_bf16 v[122:125], v[160:163], v[168:171], v[122:125]
	v_mfma_f32_16x16x32_bf16 v[110:113], v[150:153], v[176:179], v[110:113]
	v_mfma_f32_16x16x32_bf16 v[106:109], v[160:163], v[176:179], v[106:109]
	v_mfma_f32_16x16x32_bf16 v[94:97], v[150:153], v[184:187], v[94:97]
	v_mfma_f32_16x16x32_bf16 v[90:93], v[160:163], v[184:187], v[90:93]
	v_mfma_f32_16x16x32_bf16 v[78:81], v[150:153], v[192:195], v[78:81]
	v_mfma_f32_16x16x32_bf16 v[74:77], v[160:163], v[192:195], v[74:77]
	v_mfma_f32_16x16x32_bf16 v[118:121], v[196:199], v[164:167], v[118:121]
	v_mfma_f32_16x16x32_bf16 v[114:117], v[204:207], v[164:167], v[114:117]
	v_mfma_f32_16x16x32_bf16 v[102:105], v[196:199], v[172:175], v[102:105]
	v_mfma_f32_16x16x32_bf16 v[98:101], v[204:207], v[172:175], v[98:101]
	v_mfma_f32_16x16x32_bf16 v[86:89], v[196:199], v[180:183], v[86:89]
	v_mfma_f32_16x16x32_bf16 v[82:85], v[204:207], v[180:183], v[82:85]
	v_mfma_f32_16x16x32_bf16 v[70:73], v[196:199], v[188:191], v[70:73]
	v_mfma_f32_16x16x32_bf16 v[66:69], v[204:207], v[188:191], v[66:69]
	v_mfma_f32_16x16x32_bf16 v[118:121], v[200:203], v[168:171], v[118:121]
	v_mfma_f32_16x16x32_bf16 v[114:117], v[210:213], v[168:171], v[114:117]
	v_mfma_f32_16x16x32_bf16 v[102:105], v[200:203], v[176:179], v[102:105]
	v_mfma_f32_16x16x32_bf16 v[98:101], v[210:213], v[176:179], v[98:101]
	v_mfma_f32_16x16x32_bf16 v[86:89], v[200:203], v[184:187], v[86:89]
	v_mfma_f32_16x16x32_bf16 v[82:85], v[210:213], v[184:187], v[82:85]
	v_mfma_f32_16x16x32_bf16 v[70:73], v[200:203], v[192:195], v[70:73]
	v_mfma_f32_16x16x32_bf16 v[66:69], v[210:213], v[192:195], v[66:69]
	s_barrier
	s_add_i32 s38, s74, s56
	s_mov_b32 m0, s38
	s_nop 0
	global_load_lds_dwordx4 v0, s[48:49]
	s_add_i32 m0, s38, 0x2000
	s_nop 0
	global_load_lds_dwordx4 v130, s[48:49]
	s_mov_b32 m0, s9
	s_nop 0
	global_load_lds_dwordx4 v134, s[50:51]
	s_mov_b32 m0, s60
	s_nop 0
	global_load_lds_dwordx4 v132, s[50:51]
	ds_read_b128 v[164:167], v145 offset:16384
	ds_read_b128 v[168:171], v145 offset:17408
	ds_read_b128 v[172:175], v145 offset:18432
	ds_read_b128 v[176:179], v145 offset:19456
	ds_read_b128 v[180:183], v145 offset:20480
	ds_read_b128 v[184:187], v145 offset:21504
	ds_read_b128 v[188:191], v145 offset:22528
	ds_read_b128 v[192:195], v145 offset:23552
	s_waitcnt vmcnt(4)
	s_waitcnt lgkmcnt(0)
	s_barrier
	v_mfma_f32_16x16x32_bf16 v[62:65], v[146:149], v[164:167], v[62:65]
	v_mfma_f32_16x16x32_bf16 v[58:61], v[154:157], v[164:167], v[58:61]
	v_mfma_f32_16x16x32_bf16 v[46:49], v[146:149], v[172:175], v[46:49]
	v_mfma_f32_16x16x32_bf16 v[42:45], v[154:157], v[172:175], v[42:45]
	v_mfma_f32_16x16x32_bf16 v[30:33], v[146:149], v[180:183], v[30:33]
	v_mfma_f32_16x16x32_bf16 v[26:29], v[154:157], v[180:183], v[26:29]
	v_mfma_f32_16x16x32_bf16 v[14:17], v[146:149], v[188:191], v[14:17]
	v_mfma_f32_16x16x32_bf16 v[10:13], v[154:157], v[188:191], v[10:13]
	v_mfma_f32_16x16x32_bf16 v[62:65], v[150:153], v[168:171], v[62:65]
	v_mfma_f32_16x16x32_bf16 v[58:61], v[160:163], v[168:171], v[58:61]
	v_mfma_f32_16x16x32_bf16 v[46:49], v[150:153], v[176:179], v[46:49]
	v_mfma_f32_16x16x32_bf16 v[42:45], v[160:163], v[176:179], v[42:45]
	v_mfma_f32_16x16x32_bf16 v[30:33], v[150:153], v[184:187], v[30:33]
	v_mfma_f32_16x16x32_bf16 v[26:29], v[160:163], v[184:187], v[26:29]
	v_mfma_f32_16x16x32_bf16 v[14:17], v[150:153], v[192:195], v[14:17]
	v_mfma_f32_16x16x32_bf16 v[10:13], v[160:163], v[192:195], v[10:13]
	v_mfma_f32_16x16x32_bf16 v[54:57], v[196:199], v[164:167], v[54:57]
	v_mfma_f32_16x16x32_bf16 v[50:53], v[204:207], v[164:167], v[50:53]
	v_mfma_f32_16x16x32_bf16 v[38:41], v[196:199], v[172:175], v[38:41]
	v_mfma_f32_16x16x32_bf16 v[34:37], v[204:207], v[172:175], v[34:37]
	v_mfma_f32_16x16x32_bf16 v[22:25], v[196:199], v[180:183], v[22:25]
	v_mfma_f32_16x16x32_bf16 v[18:21], v[204:207], v[180:183], v[18:21]
	v_mfma_f32_16x16x32_bf16 v[6:9], v[196:199], v[188:191], v[6:9]
	v_mfma_f32_16x16x32_bf16 v[2:5], v[204:207], v[188:191], v[2:5]
	v_mfma_f32_16x16x32_bf16 v[54:57], v[200:203], v[168:171], v[54:57]
	v_mfma_f32_16x16x32_bf16 v[50:53], v[210:213], v[168:171], v[50:53]
	v_mfma_f32_16x16x32_bf16 v[38:41], v[200:203], v[176:179], v[38:41]
	v_mfma_f32_16x16x32_bf16 v[34:37], v[210:213], v[176:179], v[34:37]
	v_mfma_f32_16x16x32_bf16 v[22:25], v[200:203], v[184:187], v[22:25]
	v_mfma_f32_16x16x32_bf16 v[18:21], v[210:213], v[184:187], v[18:21]
	v_mfma_f32_16x16x32_bf16 v[6:9], v[200:203], v[192:195], v[6:9]
	v_mfma_f32_16x16x32_bf16 v[2:5], v[210:213], v[192:195], v[2:5]
	s_barrier
; #define PG8_STAGE(bufoff, gbase, voff) do { _Pragma("unroll") for (int _i = 0; _i < 2; ++_i) \
;         __builtin_amdgcn_global_load_lds((const unsigned*)((const char*)(gbase) + (voff)[_i]), (LAS unsigned*)(lds + (bufoff) + ldsw + _i * 8192), 16, 0, 0); } while (0)
; #define PG8_LDA(dst, b, h) do { _Pragma("unroll") for (int m = 0; m < 4; ++m) _Pragma("unroll") for (int k = 0; k < 2; ++k) dst[m][k] = *(const LAS bf16x8*)(lds + PG8_SA(b, h) + aoff + m * 2048 + k * 1024); } while (0)
; #define PG8_LDB(dst, b, h) do { _Pragma("unroll") for (int n = 0; n < 2; ++n) _Pragma("unroll") for (int k = 0; k < 2; ++k) dst[n][k] = *(const LAS bf16x8*)(lds + PG8_SB(b, h) + boff + n * 2048 + k * 1024); } while (0)
; #define PG8_MMA(ai, bj, At, Bt) do { __builtin_amdgcn_s_setprio(1); _Pragma("unroll") for (int m = 0; m < 4; ++m) _Pragma("unroll") for (int n = 0; n < 2; ++n) _Pragma("unroll") for (int k = 0; k < 2; ++k) \
;         acc[ai][bj][m][n] = __builtin_amdgcn_mfma_f32_16x16x32_bf16(Bt[n][k], At[m][k], acc[ai][bj][m][n], 0, 0, 0); __builtin_amdgcn_s_setprio(0); } while (0)
; #define PG8_WAIT_V(n) asm volatile("s_waitcnt vmcnt(" #n ")" ::: "memory")
; #define PG8_WAIT_L(n) asm volatile("s_waitcnt lgkmcnt(" #n ")" ::: "memory")
; #define PG8_BAR __builtin_amdgcn_s_barrier()
; #define PG8_SCHED __builtin_amdgcn_sched_barrier(0)
; template <class Epi, class Sched>
; __device__ __forceinline__ void gemm_phase(LAS unsigned char* lds, const Gemm g, const Sched& S, const Epi& E) {
;     ...
;             PG8_LDB(B0, 1, 0); PG8_SCHED; PG8_LDA(At, 1, 0); PG8_STAGE(PG8_SA(0, 1), a2 + hstep, voffA);
;             PG8_WAIT_L(8); PG8_BAR; PG8_WAIT_L(0); PG8_MMA(0, 0, At, B0); PG8_BAR; PG8_SCHED;
;             PG8_LDB(B1, 1, 1); PG8_STAGE(PG8_SB(1, 0), b3, voffB);
;             PG8_BAR; PG8_WAIT_L(0); PG8_MMA(0, 1, At, B1); PG8_BAR;
;             PG8_LDA(At, 1, 1); PG8_STAGE(PG8_SA(1, 0), a3, voffA);
;             PG8_BAR; PG8_WAIT_L(0); PG8_MMA(1, 0, At, B0); PG8_BAR; PG8_SCHED;
;             PG8_STAGE(PG8_SB(1, 1), b3 + hstep, voffB);
;             PG8_WAIT_V(6); PG8_BAR; PG8_MMA(1, 1, At, B1); PG8_BAR;
	s_add_u32 s38, s48, 0x80000
	s_addc_u32 s39, s49, 0
	s_add_i32 s74, s75, s56
	s_mov_b32 m0, s74
	s_nop 0
	global_load_lds_dwordx4 v0, s[38:39]
	s_add_i32 m0, s74, 0x2000
	s_nop 0
	global_load_lds_dwordx4 v130, s[38:39]
	s_add_u32 s38, s50, 0x80000
	s_addc_u32 s39, s51, 0
	s_mov_b32 m0, s61
	s_nop 0
	global_load_lds_dwordx4 v134, s[38:39]
	s_mov_b32 m0, s62
	s_nop 0
	global_load_lds_dwordx4 v132, s[38:39]
	s_add_i32 s74, 0, 0x18000
	ds_read_b128 v[146:149], v226 offset:32768
	ds_read_b128 v[150:153], v226 offset:33792
	ds_read_b128 v[154:157], v226 offset:34816
	ds_read_b128 v[160:163], v226 offset:35840
	ds_read_b128 v[164:167], v145 offset:32768
	ds_read_b128 v[168:171], v145 offset:33792
	ds_read_b128 v[172:175], v145 offset:34816
	ds_read_b128 v[176:179], v145 offset:35840
	ds_read_b128 v[180:183], v145 offset:36864
	ds_read_b128 v[184:187], v145 offset:37888
	ds_read_b128 v[188:191], v145 offset:38912
	ds_read_b128 v[192:195], v145 offset:39936
	s_nop 0
	ds_read_b128 v[196:199], v226 offset:49152
	ds_read_b128 v[200:203], v226 offset:50176
	ds_read_b128 v[204:207], v226 offset:51200
	ds_read_b128 v[210:213], v226 offset:52224
	s_waitcnt lgkmcnt(4)
	s_barrier
	s_waitcnt lgkmcnt(0)
	v_mfma_f32_16x16x32_bf16 v[126:129], v[146:149], v[164:167], v[126:129]
	v_mfma_f32_16x16x32_bf16 v[122:125], v[154:157], v[164:167], v[122:125]
	v_mfma_f32_16x16x32_bf16 v[110:113], v[146:149], v[172:175], v[110:113]
	v_mfma_f32_16x16x32_bf16 v[106:109], v[154:157], v[172:175], v[106:109]
	v_mfma_f32_16x16x32_bf16 v[94:97], v[146:149], v[180:183], v[94:97]
	v_mfma_f32_16x16x32_bf16 v[90:93], v[154:157], v[180:183], v[90:93]
	v_mfma_f32_16x16x32_bf16 v[78:81], v[146:149], v[188:191], v[78:81]
	v_mfma_f32_16x16x32_bf16 v[74:77], v[154:157], v[188:191], v[74:77]
	v_mfma_f32_16x16x32_bf16 v[126:129], v[150:153], v[168:171], v[126:129]
	v_mfma_f32_16x16x32_bf16 v[122:125], v[160:163], v[168:171], v[122:125]
	v_mfma_f32_16x16x32_bf16 v[110:113], v[150:153], v[176:179], v[110:113]
	v_mfma_f32_16x16x32_bf16 v[106:109], v[160:163], v[176:179], v[106:109]
	v_mfma_f32_16x16x32_bf16 v[94:97], v[150:153], v[184:187], v[94:97]
	v_mfma_f32_16x16x32_bf16 v[90:93], v[160:163], v[184:187], v[90:93]
	v_mfma_f32_16x16x32_bf16 v[78:81], v[150:153], v[192:195], v[78:81]
	v_mfma_f32_16x16x32_bf16 v[74:77], v[160:163], v[192:195], v[74:77]
	v_mfma_f32_16x16x32_bf16 v[118:121], v[196:199], v[164:167], v[118:121]
	v_mfma_f32_16x16x32_bf16 v[114:117], v[204:207], v[164:167], v[114:117]
	v_mfma_f32_16x16x32_bf16 v[102:105], v[196:199], v[172:175], v[102:105]
	v_mfma_f32_16x16x32_bf16 v[98:101], v[204:207], v[172:175], v[98:101]
	v_mfma_f32_16x16x32_bf16 v[86:89], v[196:199], v[180:183], v[86:89]
	v_mfma_f32_16x16x32_bf16 v[82:85], v[204:207], v[180:183], v[82:85]
	v_mfma_f32_16x16x32_bf16 v[70:73], v[196:199], v[188:191], v[70:73]
	v_mfma_f32_16x16x32_bf16 v[66:69], v[204:207], v[188:191], v[66:69]
	v_mfma_f32_16x16x32_bf16 v[118:121], v[200:203], v[168:171], v[118:121]
	v_mfma_f32_16x16x32_bf16 v[114:117], v[210:213], v[168:171], v[114:117]
	v_mfma_f32_16x16x32_bf16 v[102:105], v[200:203], v[176:179], v[102:105]
	v_mfma_f32_16x16x32_bf16 v[98:101], v[210:213], v[176:179], v[98:101]
	v_mfma_f32_16x16x32_bf16 v[86:89], v[200:203], v[184:187], v[86:89]
	v_mfma_f32_16x16x32_bf16 v[82:85], v[210:213], v[184:187], v[82:85]
	v_mfma_f32_16x16x32_bf16 v[70:73], v[200:203], v[192:195], v[70:73]
	v_mfma_f32_16x16x32_bf16 v[66:69], v[210:213], v[192:195], v[66:69]
	s_barrier
	s_add_i32 s38, s74, s56
	s_add_u32 s100, s48, s36
	s_addc_u32 s101, s49, s37
	s_mov_b32 m0, s38
	s_nop 0
	global_load_lds_dwordx4 v0, s[100:101]
	s_add_i32 m0, s38, 0x2000
	s_nop 0
	global_load_lds_dwordx4 v130, s[100:101]
	s_mov_b32 m0, s64
	s_add_u32 s100, s50, s36
	s_addc_u32 s101, s51, s37
	global_load_lds_dwordx4 v134, s[100:101]
	s_mov_b32 m0, s65
	s_nop 0
	global_load_lds_dwordx4 v132, s[100:101]
	ds_read_b128 v[164:167], v145 offset:49152
	ds_read_b128 v[168:171], v145 offset:50176
	ds_read_b128 v[172:175], v145 offset:51200
	ds_read_b128 v[176:179], v145 offset:52224
	ds_read_b128 v[180:183], v145 offset:53248
	ds_read_b128 v[184:187], v145 offset:54272
	ds_read_b128 v[188:191], v145 offset:55296
	ds_read_b128 v[192:195], v145 offset:56320
	s_waitcnt vmcnt(4)
	s_waitcnt lgkmcnt(0)
	s_barrier
	v_mfma_f32_16x16x32_bf16 v[62:65], v[146:149], v[164:167], v[62:65]
	v_mfma_f32_16x16x32_bf16 v[58:61], v[154:157], v[164:167], v[58:61]
	v_mfma_f32_16x16x32_bf16 v[46:49], v[146:149], v[172:175], v[46:49]
	v_mfma_f32_16x16x32_bf16 v[42:45], v[154:157], v[172:175], v[42:45]
	v_mfma_f32_16x16x32_bf16 v[30:33], v[146:149], v[180:183], v[30:33]
	v_mfma_f32_16x16x32_bf16 v[26:29], v[154:157], v[180:183], v[26:29]
	v_mfma_f32_16x16x32_bf16 v[14:17], v[146:149], v[188:191], v[14:17]
	v_mfma_f32_16x16x32_bf16 v[10:13], v[154:157], v[188:191], v[10:13]
	v_mfma_f32_16x16x32_bf16 v[62:65], v[150:153], v[168:171], v[62:65]
	v_mfma_f32_16x16x32_bf16 v[58:61], v[160:163], v[168:171], v[58:61]
	v_mfma_f32_16x16x32_bf16 v[46:49], v[150:153], v[176:179], v[46:49]
	v_mfma_f32_16x16x32_bf16 v[42:45], v[160:163], v[176:179], v[42:45]
	v_mfma_f32_16x16x32_bf16 v[30:33], v[150:153], v[184:187], v[30:33]
	v_mfma_f32_16x16x32_bf16 v[26:29], v[160:163], v[184:187], v[26:29]
	v_mfma_f32_16x16x32_bf16 v[14:17], v[150:153], v[192:195], v[14:17]
	v_mfma_f32_16x16x32_bf16 v[10:13], v[160:163], v[192:195], v[10:13]
	s_add_u32 s38, s48, 0x80080
	s_addc_u32 s39, s49, 0
	s_add_i32 s48, s56, 0x1c000
	s_mov_b32 m0, s48
	s_nop 0
	global_load_lds_dwordx4 v0, s[38:39]
	s_add_i32 m0, s48, 0x2000
	s_nop 0
	global_load_lds_dwordx4 v130, s[38:39]
	v_mfma_f32_16x16x32_bf16 v[54:57], v[196:199], v[164:167], v[54:57]
	v_mfma_f32_16x16x32_bf16 v[50:53], v[204:207], v[164:167], v[50:53]
	v_mfma_f32_16x16x32_bf16 v[38:41], v[196:199], v[172:175], v[38:41]
	v_mfma_f32_16x16x32_bf16 v[34:37], v[204:207], v[172:175], v[34:37]
	v_mfma_f32_16x16x32_bf16 v[22:25], v[196:199], v[180:183], v[22:25]
	v_mfma_f32_16x16x32_bf16 v[18:21], v[204:207], v[180:183], v[18:21]
	v_mfma_f32_16x16x32_bf16 v[6:9], v[196:199], v[188:191], v[6:9]
	v_mfma_f32_16x16x32_bf16 v[2:5], v[204:207], v[188:191], v[2:5]
	v_mfma_f32_16x16x32_bf16 v[54:57], v[200:203], v[168:171], v[54:57]
	v_mfma_f32_16x16x32_bf16 v[50:53], v[210:213], v[168:171], v[50:53]
	v_mfma_f32_16x16x32_bf16 v[38:41], v[200:203], v[176:179], v[38:41]
	v_mfma_f32_16x16x32_bf16 v[34:37], v[210:213], v[176:179], v[34:37]
	v_mfma_f32_16x16x32_bf16 v[22:25], v[200:203], v[184:187], v[22:25]
	v_mfma_f32_16x16x32_bf16 v[18:21], v[210:213], v[184:187], v[18:21]
	v_mfma_f32_16x16x32_bf16 v[6:9], v[200:203], v[192:195], v[6:9]
	v_mfma_f32_16x16x32_bf16 v[2:5], v[210:213], v[192:195], v[2:5]
	s_add_i32 s73, s73, 2
	s_add_u32 s71, s71, 0x100
	s_addc_u32 s72, s72, 0
	s_add_u32 s46, s46, 0x100
	s_addc_u32 s47, s47, 0
	s_cmp_gt_u32 s73, 29
	s_barrier
	s_cbranch_scc0 .LBB0_73
	s_cmpk_gt_u32 s52, 0xff
	s_cbranch_scc1 .Ldsx0_73
	s_cmp_lg_u64 s[40:41], 0
	s_cbranch_scc1 .Ldsx0_73
	s_barrier
; __device__ __forceinline__ unsigned cvt_pk_bf16(float lo, float hi) { unsigned r; asm("v_cvt_pk_bf16_f32 %0, %1, %2" : "=v"(r) : "v"(lo), "v"(hi)); return r; }
;     __device__ __forceinline__ void operator()(const f32x4 (&acc)[2][2][4][2], const Unit& u, int wr, int wc, int fr, int fq) const {
;         const int row0 = u.pm * BM + wr * 64 + fr, col0 = u.pn * BM + wc * 32 + 8 * fq;
; #pragma unroll
;         for (int ai = 0; ai < 2; ++ai)
; #pragma unroll
;             for (int m = 0; m < 4; ++m) { bf16_t* rowp = O + (size_t)(row0 + ai * HALF + m * 16) * ldc + col0;
; #pragma unroll
;                 for (int bj = 0; bj < 2; ++bj) { f32x4 v0 = acc[ai][bj][m][0], v1 = acc[ai][bj][m][1];
;                     if (ACT == 1) {
; #pragma unroll
;                         for (int j = 0; j < 4; ++j) { float a = fmaxf(v0[j], 0.f), b = fmaxf(v1[j], 0.f); v0[j] = a * a; v1[j] = b * b; } }
;                     u32x4 w; w.x = cvt_pk_bf16(v0[0], v0[1]); w.y = cvt_pk_bf16(v0[2], v0[3]); w.z = cvt_pk_bf16(v1[0], v1[1]); w.w = cvt_pk_bf16(v1[2], v1[3]);
;                     if (ACT == 1) __builtin_nontemporal_store(w, (u32x4*)(rowp + bj * HALF));
;                     else *(u32x4*)(rowp + bj * HALF) = w; } }
.Ldsx0_73:
	v_lshl_add_u32 v146, s8, 8, v142
	v_max_f32_e32 v122, v122, v122
	v_ashrrev_i32_e32 v147, 31, v146
	v_max_f32_e32 v122, 0, v122
	v_max_f32_e32 v123, v123, v123
	v_max_f32_e32 v124, v124, v124
	v_lshl_or_b32 v140, s68, 8, v144
	v_lshlrev_b64 v[148:149], 14, v[146:147]
	v_mul_f32_e32 v147, v122, v122
	v_max_f32_e32 v122, v127, v127
	v_max_f32_e32 v123, 0, v123
	v_max_f32_e32 v124, 0, v124
	v_ashrrev_i32_e32 v141, 31, v140
	v_max_f32_e32 v126, v126, v126
	v_max_f32_e32 v122, 0, v122
	v_mul_f32_e32 v127, v123, v123
	v_max_f32_e32 v123, v128, v128
	v_mul_f32_e32 v128, v124, v124
	v_max_f32_e32 v124, v129, v129
	v_max_f32_e32 v125, v125, v125
	v_lshl_add_u64 v[148:149], s[24:25], 0, v[148:149]
	v_lshlrev_b64 v[150:151], 1, v[140:141]
	v_max_f32_e32 v126, 0, v126
	v_mul_f32_e32 v122, v122, v122
	v_max_f32_e32 v123, 0, v123
	v_max_f32_e32 v124, 0, v124
	v_max_f32_e32 v125, 0, v125
	v_max_f32_e32 v114, v114, v114
	v_lshl_add_u64 v[140:141], v[148:149], 0, v[150:151]
	v_mul_f32_e32 v126, v126, v126
	v_mul_f32_e32 v123, v123, v123
	v_mul_f32_e32 v124, v124, v124
	v_mul_f32_e32 v125, v125, v125
	v_cvt_pk_bf16_f32 v122, v126, v122
	v_max_f32_e32 v114, 0, v114
	v_max_f32_e32 v115, v115, v115
	v_max_f32_e32 v116, v116, v116
	v_cvt_pk_bf16_f32 v123, v123, v124
	v_cvt_pk_bf16_f32 v124, v147, v127
	v_cvt_pk_bf16_f32 v125, v128, v125
	global_store_dwordx4 v[140:141], v[122:125], off nt
	v_max_f32_e32 v115, 0, v115
	v_max_f32_e32 v116, 0, v116
	v_mul_f32_e32 v122, v114, v114
	v_max_f32_e32 v114, v119, v119
	v_max_f32_e32 v118, v118, v118
	v_max_f32_e32 v114, 0, v114
	v_mul_f32_e32 v119, v115, v115
	v_max_f32_e32 v115, v120, v120
	v_mul_f32_e32 v120, v116, v116
	v_max_f32_e32 v116, v121, v121
	v_max_f32_e32 v117, v117, v117
	v_max_f32_e32 v118, 0, v118
	v_mul_f32_e32 v114, v114, v114
	v_max_f32_e32 v115, 0, v115
	v_max_f32_e32 v116, 0, v116
	v_max_f32_e32 v117, 0, v117
	v_mul_f32_e32 v118, v118, v118
	v_mul_f32_e32 v115, v115, v115
	v_mul_f32_e32 v116, v116, v116
	v_mul_f32_e32 v117, v117, v117
	v_cvt_pk_bf16_f32 v114, v118, v114
	v_max_f32_e32 v106, v106, v106
	v_cvt_pk_bf16_f32 v115, v115, v116
	v_cvt_pk_bf16_f32 v116, v122, v119
	v_cvt_pk_bf16_f32 v117, v120, v117
	global_store_dwordx4 v[140:141], v[114:117], off offset:256 nt
	v_max_f32_e32 v106, 0, v106
	v_max_f32_e32 v107, v107, v107
	v_or_b32_e32 v114, 16, v146
	v_max_f32_e32 v108, v108, v108
	v_ashrrev_i32_e32 v115, 31, v114
	v_mul_f32_e32 v116, v106, v106
	v_max_f32_e32 v106, v111, v111
	v_max_f32_e32 v107, 0, v107
	v_max_f32_e32 v108, 0, v108
	v_lshlrev_b64 v[114:115], 14, v[114:115]
	v_max_f32_e32 v110, v110, v110
	v_max_f32_e32 v106, 0, v106
	v_mul_f32_e32 v111, v107, v107
	v_max_f32_e32 v107, v112, v112
	v_mul_f32_e32 v112, v108, v108
	v_max_f32_e32 v108, v113, v113
	v_max_f32_e32 v109, v109, v109
	v_lshl_add_u64 v[114:115], s[24:25], 0, v[114:115]
	v_max_f32_e32 v110, 0, v110
	v_mul_f32_e32 v106, v106, v106
	v_max_f32_e32 v107, 0, v107
	v_max_f32_e32 v108, 0, v108
	v_max_f32_e32 v109, 0, v109
	v_max_f32_e32 v98, v98, v98
	v_lshl_add_u64 v[114:115], v[114:115], 0, v[150:151]
	v_mul_f32_e32 v110, v110, v110
	v_mul_f32_e32 v107, v107, v107
	v_mul_f32_e32 v108, v108, v108
	v_mul_f32_e32 v109, v109, v109
	v_cvt_pk_bf16_f32 v106, v110, v106
	v_max_f32_e32 v98, 0, v98
	v_max_f32_e32 v99, v99, v99
	v_max_f32_e32 v100, v100, v100
	v_cvt_pk_bf16_f32 v107, v107, v108
	v_cvt_pk_bf16_f32 v108, v116, v111
	v_cvt_pk_bf16_f32 v109, v112, v109
	global_store_dwordx4 v[114:115], v[106:109], off nt
	v_max_f32_e32 v99, 0, v99
	v_max_f32_e32 v100, 0, v100
	v_mul_f32_e32 v106, v98, v98
	v_max_f32_e32 v98, v103, v103
	v_max_f32_e32 v102, v102, v102
	v_max_f32_e32 v98, 0, v98
	v_mul_f32_e32 v103, v99, v99
	v_max_f32_e32 v99, v104, v104
	v_mul_f32_e32 v104, v100, v100
	v_max_f32_e32 v100, v105, v105
	v_max_f32_e32 v101, v101, v101
	v_max_f32_e32 v102, 0, v102
	v_mul_f32_e32 v98, v98, v98
	v_max_f32_e32 v99, 0, v99
	v_max_f32_e32 v100, 0, v100
	v_max_f32_e32 v101, 0, v101
	v_mul_f32_e32 v102, v102, v102
	v_mul_f32_e32 v99, v99, v99
	v_mul_f32_e32 v100, v100, v100
	v_mul_f32_e32 v101, v101, v101
	v_cvt_pk_bf16_f32 v98, v102, v98
	v_max_f32_e32 v90, v90, v90
	v_cvt_pk_bf16_f32 v99, v99, v100
	v_cvt_pk_bf16_f32 v100, v106, v103
	v_cvt_pk_bf16_f32 v101, v104, v101
	global_store_dwordx4 v[114:115], v[98:101], off offset:256 nt
	v_max_f32_e32 v90, 0, v90
	v_max_f32_e32 v91, v91, v91
	v_or_b32_e32 v98, 32, v146
	v_max_f32_e32 v92, v92, v92
	v_ashrrev_i32_e32 v99, 31, v98
	v_mul_f32_e32 v100, v90, v90
	v_max_f32_e32 v90, v95, v95
	v_max_f32_e32 v91, 0, v91
	v_max_f32_e32 v92, 0, v92
	v_lshlrev_b64 v[98:99], 14, v[98:99]
	v_max_f32_e32 v94, v94, v94
	v_max_f32_e32 v90, 0, v90
	v_mul_f32_e32 v95, v91, v91
	v_max_f32_e32 v91, v96, v96
	v_mul_f32_e32 v96, v92, v92
	v_max_f32_e32 v92, v97, v97
	v_max_f32_e32 v93, v93, v93
	v_lshl_add_u64 v[98:99], s[24:25], 0, v[98:99]
	v_max_f32_e32 v94, 0, v94
	v_mul_f32_e32 v90, v90, v90
	v_max_f32_e32 v91, 0, v91
	v_max_f32_e32 v92, 0, v92
	v_max_f32_e32 v93, 0, v93
	v_max_f32_e32 v82, v82, v82
	v_lshl_add_u64 v[98:99], v[98:99], 0, v[150:151]
	v_mul_f32_e32 v94, v94, v94
	v_mul_f32_e32 v91, v91, v91
	v_mul_f32_e32 v92, v92, v92
	v_mul_f32_e32 v93, v93, v93
	v_cvt_pk_bf16_f32 v90, v94, v90
	v_max_f32_e32 v82, 0, v82
	v_max_f32_e32 v83, v83, v83
	v_max_f32_e32 v84, v84, v84
	v_cvt_pk_bf16_f32 v91, v91, v92
	v_cvt_pk_bf16_f32 v92, v100, v95
	v_cvt_pk_bf16_f32 v93, v96, v93
	global_store_dwordx4 v[98:99], v[90:93], off nt
	v_max_f32_e32 v83, 0, v83
	v_max_f32_e32 v84, 0, v84
	v_mul_f32_e32 v90, v82, v82
	v_max_f32_e32 v82, v87, v87
	v_max_f32_e32 v86, v86, v86
	v_max_f32_e32 v82, 0, v82
; __device__ __forceinline__ unsigned cvt_pk_bf16(float lo, float hi) { unsigned r; asm("v_cvt_pk_bf16_f32 %0, %1, %2" : "=v"(r) : "v"(lo), "v"(hi)); return r; }
;     __device__ __forceinline__ void operator()(const f32x4 (&acc)[2][2][4][2], const Unit& u, int wr, int wc, int fr, int fq) const {
;     ...
;             for (int m = 0; m < 4; ++m) { bf16_t* rowp = O + (size_t)(row0 + ai * HALF + m * 16) * ldc + col0;
; #pragma unroll
;                 for (int bj = 0; bj < 2; ++bj) { f32x4 v0 = acc[ai][bj][m][0], v1 = acc[ai][bj][m][1];
;                     if (ACT == 1) {
; #pragma unroll
;                         for (int j = 0; j < 4; ++j) { float a = fmaxf(v0[j], 0.f), b = fmaxf(v1[j], 0.f); v0[j] = a * a; v1[j] = b * b; } }
;                     u32x4 w; w.x = cvt_pk_bf16(v0[0], v0[1]); w.y = cvt_pk_bf16(v0[2], v0[3]); w.z = cvt_pk_bf16(v1[0], v1[1]); w.w = cvt_pk_bf16(v1[2], v1[3]);
;                     if (ACT == 1) __builtin_nontemporal_store(w, (u32x4*)(rowp + bj * HALF));
;                     else *(u32x4*)(rowp + bj * HALF) = w; } }
	v_mul_f32_e32 v87, v83, v83
	v_max_f32_e32 v83, v88, v88
	v_mul_f32_e32 v88, v84, v84
	v_max_f32_e32 v84, v89, v89
	v_max_f32_e32 v85, v85, v85
	v_max_f32_e32 v86, 0, v86
	v_mul_f32_e32 v82, v82, v82
	v_max_f32_e32 v83, 0, v83
	v_max_f32_e32 v84, 0, v84
	v_max_f32_e32 v85, 0, v85
	v_mul_f32_e32 v86, v86, v86
	v_mul_f32_e32 v83, v83, v83
	v_mul_f32_e32 v84, v84, v84
	v_mul_f32_e32 v85, v85, v85
	v_cvt_pk_bf16_f32 v82, v86, v82
	v_max_f32_e32 v74, v74, v74
	v_cvt_pk_bf16_f32 v83, v83, v84
	v_cvt_pk_bf16_f32 v84, v90, v87
	v_cvt_pk_bf16_f32 v85, v88, v85
	global_store_dwordx4 v[98:99], v[82:85], off offset:256 nt
	v_max_f32_e32 v74, 0, v74
	v_max_f32_e32 v75, v75, v75
	v_or_b32_e32 v82, 48, v146
	v_max_f32_e32 v76, v76, v76
	v_ashrrev_i32_e32 v83, 31, v82
	v_mul_f32_e32 v84, v74, v74
	v_max_f32_e32 v74, v79, v79
	v_max_f32_e32 v75, 0, v75
	v_max_f32_e32 v76, 0, v76
	v_lshlrev_b64 v[82:83], 14, v[82:83]
	v_max_f32_e32 v78, v78, v78
	v_max_f32_e32 v74, 0, v74
	v_mul_f32_e32 v79, v75, v75
	v_max_f32_e32 v75, v80, v80
	v_mul_f32_e32 v80, v76, v76
	v_max_f32_e32 v76, v81, v81
	v_max_f32_e32 v77, v77, v77
	v_lshl_add_u64 v[82:83], s[24:25], 0, v[82:83]
	v_max_f32_e32 v78, 0, v78
	v_mul_f32_e32 v74, v74, v74
	v_max_f32_e32 v75, 0, v75
	v_max_f32_e32 v76, 0, v76
	v_max_f32_e32 v77, 0, v77
	v_max_f32_e32 v66, v66, v66
	v_max_f32_e32 v67, v67, v67
	v_max_f32_e32 v68, v68, v68
	v_lshl_add_u64 v[82:83], v[82:83], 0, v[150:151]
	v_mul_f32_e32 v78, v78, v78
	v_mul_f32_e32 v75, v75, v75
	v_mul_f32_e32 v76, v76, v76
	v_mul_f32_e32 v77, v77, v77
	v_cvt_pk_bf16_f32 v74, v78, v74
	v_max_f32_e32 v66, 0, v66
	v_max_f32_e32 v67, 0, v67
	v_max_f32_e32 v68, 0, v68
	v_cvt_pk_bf16_f32 v75, v75, v76
	v_cvt_pk_bf16_f32 v76, v84, v79
	v_cvt_pk_bf16_f32 v77, v80, v77
	global_store_dwordx4 v[82:83], v[74:77], off nt
	v_max_f32_e32 v69, v69, v69
	v_max_f32_e32 v70, v70, v70
	v_mul_f32_e32 v74, v66, v66
	v_max_f32_e32 v66, v71, v71
	v_mul_f32_e32 v71, v67, v67
	v_max_f32_e32 v67, v72, v72
	v_mul_f32_e32 v72, v68, v68
	v_max_f32_e32 v68, v73, v73
	v_max_f32_e32 v67, 0, v67
	v_max_f32_e32 v68, 0, v68
	v_max_f32_e32 v66, 0, v66
	v_mul_f32_e32 v67, v67, v67
	v_max_f32_e32 v69, 0, v69
	v_mul_f32_e32 v68, v68, v68
	v_max_f32_e32 v58, v58, v58
	v_max_f32_e32 v70, 0, v70
	v_mul_f32_e32 v66, v66, v66
	v_mul_f32_e32 v69, v69, v69
	v_cvt_pk_bf16_f32 v67, v67, v68
	v_cvt_pk_bf16_f32 v68, v74, v71
	v_max_f32_e32 v58, 0, v58
	v_max_f32_e32 v59, v59, v59
	v_max_f32_e32 v60, v60, v60
	v_mul_f32_e32 v70, v70, v70
	v_cvt_pk_bf16_f32 v66, v70, v66
	v_cvt_pk_bf16_f32 v69, v72, v69
	global_store_dwordx4 v[82:83], v[66:69], off offset:256 nt
	v_max_f32_e32 v62, v62, v62
	v_max_f32_e32 v59, 0, v59
	v_mul_f32_e32 v68, v58, v58
	v_max_f32_e32 v58, v63, v63
	v_max_f32_e32 v60, 0, v60
	v_max_f32_e32 v62, 0, v62
	v_max_f32_e32 v58, 0, v58
	v_mul_f32_e32 v63, v59, v59
	v_max_f32_e32 v59, v64, v64
	v_mul_f32_e32 v64, v60, v60
	v_max_f32_e32 v60, v65, v65
	v_mul_f32_e32 v62, v62, v62
	v_mul_f32_e32 v58, v58, v58
	v_max_f32_e32 v59, 0, v59
	v_max_f32_e32 v60, 0, v60
	v_max_f32_e32 v61, v61, v61
	s_mov_b32 s8, 0x200000
	v_mul_f32_e32 v59, v59, v59
	v_max_f32_e32 v61, 0, v61
	v_mul_f32_e32 v60, v60, v60
	v_cvt_pk_bf16_f32 v58, v62, v58
	v_add_co_u32_e32 v62, vcc, s8, v140
	v_max_f32_e32 v50, v50, v50
	v_max_f32_e32 v51, v51, v51
	v_max_f32_e32 v52, v52, v52
	v_mul_f32_e32 v61, v61, v61
	v_cvt_pk_bf16_f32 v59, v59, v60
	v_cvt_pk_bf16_f32 v60, v68, v63
	v_addc_co_u32_e32 v63, vcc, 0, v141, vcc
	v_max_f32_e32 v50, 0, v50
	v_max_f32_e32 v51, 0, v51
	v_max_f32_e32 v52, 0, v52
	v_cvt_pk_bf16_f32 v61, v64, v61
	global_store_dwordx4 v[62:63], v[58:61], off nt
	v_max_f32_e32 v53, v53, v53
	s_mov_b64 s[38:39], 0x200000
	v_mul_f32_e32 v58, v50, v50
	v_max_f32_e32 v50, v55, v55
	v_mul_f32_e32 v55, v51, v51
	v_max_f32_e32 v51, v56, v56
	v_mul_f32_e32 v56, v52, v52
	v_max_f32_e32 v52, v57, v57
	v_max_f32_e32 v51, 0, v51
	v_max_f32_e32 v52, 0, v52
	v_max_f32_e32 v54, v54, v54
	v_max_f32_e32 v50, 0, v50
	v_mul_f32_e32 v51, v51, v51
	v_max_f32_e32 v53, 0, v53
	v_mul_f32_e32 v52, v52, v52
	v_max_f32_e32 v42, v42, v42
	v_lshl_add_u64 v[66:67], v[140:141], 0, s[38:39]
	v_max_f32_e32 v54, 0, v54
	v_mul_f32_e32 v50, v50, v50
	v_mul_f32_e32 v53, v53, v53
	v_cvt_pk_bf16_f32 v51, v51, v52
	v_cvt_pk_bf16_f32 v52, v58, v55
	v_max_f32_e32 v42, 0, v42
	v_max_f32_e32 v43, v43, v43
	v_max_f32_e32 v44, v44, v44
	v_mul_f32_e32 v54, v54, v54
	v_cvt_pk_bf16_f32 v50, v54, v50
	v_cvt_pk_bf16_f32 v53, v56, v53
	global_store_dwordx4 v[66:67], v[50:53], off offset:256 nt
	v_max_f32_e32 v46, v46, v46
	v_max_f32_e32 v43, 0, v43
	v_mul_f32_e32 v52, v42, v42
	v_max_f32_e32 v42, v47, v47
	v_max_f32_e32 v44, 0, v44
	v_max_f32_e32 v46, 0, v46
	v_max_f32_e32 v42, 0, v42
	v_mul_f32_e32 v47, v43, v43
	v_max_f32_e32 v43, v48, v48
	v_mul_f32_e32 v48, v44, v44
	v_max_f32_e32 v44, v49, v49
	v_mul_f32_e32 v46, v46, v46
	v_mul_f32_e32 v42, v42, v42
	v_max_f32_e32 v43, 0, v43
	v_max_f32_e32 v44, 0, v44
	v_max_f32_e32 v45, v45, v45
	s_mov_b32 s8, 0x240000
	v_mul_f32_e32 v43, v43, v43
	v_max_f32_e32 v45, 0, v45
	v_mul_f32_e32 v44, v44, v44
	v_cvt_pk_bf16_f32 v42, v46, v42
	v_add_co_u32_e32 v46, vcc, s8, v140
; __device__ __forceinline__ unsigned cvt_pk_bf16(float lo, float hi) { unsigned r; asm("v_cvt_pk_bf16_f32 %0, %1, %2" : "=v"(r) : "v"(lo), "v"(hi)); return r; }
; #define PG8_WAIT_V(n) asm volatile("s_waitcnt vmcnt(" #n ")" ::: "memory")
; #define PG8_BAR __builtin_amdgcn_s_barrier()
;     __device__ __forceinline__ void operator()(const f32x4 (&acc)[2][2][4][2], const Unit& u, int wr, int wc, int fr, int fq) const {
;     ...
;             for (int m = 0; m < 4; ++m) { bf16_t* rowp = O + (size_t)(row0 + ai * HALF + m * 16) * ldc + col0;
; #pragma unroll
;                 for (int bj = 0; bj < 2; ++bj) { f32x4 v0 = acc[ai][bj][m][0], v1 = acc[ai][bj][m][1];
;                     if (ACT == 1) {
; #pragma unroll
;                         for (int j = 0; j < 4; ++j) { float a = fmaxf(v0[j], 0.f), b = fmaxf(v1[j], 0.f); v0[j] = a * a; v1[j] = b * b; } }
;                     u32x4 w; w.x = cvt_pk_bf16(v0[0], v0[1]); w.y = cvt_pk_bf16(v0[2], v0[3]); w.z = cvt_pk_bf16(v1[0], v1[1]); w.w = cvt_pk_bf16(v1[2], v1[3]);
;                     if (ACT == 1) __builtin_nontemporal_store(w, (u32x4*)(rowp + bj * HALF));
;                     else *(u32x4*)(rowp + bj * HALF) = w; } }
; template <class Epi, class Sched>
; __device__ __forceinline__ void gemm_phase(LAS unsigned char* lds, const Gemm g, const Sched& S, const Epi& E) {
;     ...
;         E(acc, cur, wr, wc, fr, fq);
;         if (!has_next) break;
; #pragma unroll
;         for (int a = 0; a < 2; ++a)
; #pragma unroll
;             for (int b = 0; b < 2; ++b)
; #pragma unroll
;                 for (int m = 0; m < 4; ++m)
; #pragma unroll
;                     for (int n = 0; n < 2; ++n) acc[a][b][m][n] = (f32x4){0.f, 0.f, 0.f, 0.f};
;         cur = nxt; cA = nA; cB = nB; ++ui;
;     }
;     PG8_WAIT_V(0);
;     if (wr == 0) PG8_BAR;
;     PG8_BAR;
	v_max_f32_e32 v34, v34, v34
	v_max_f32_e32 v35, v35, v35
	v_max_f32_e32 v36, v36, v36
	v_mul_f32_e32 v45, v45, v45
	v_cvt_pk_bf16_f32 v43, v43, v44
	v_cvt_pk_bf16_f32 v44, v52, v47
	v_addc_co_u32_e32 v47, vcc, 0, v141, vcc
	v_max_f32_e32 v34, 0, v34
	v_max_f32_e32 v35, 0, v35
	v_max_f32_e32 v36, 0, v36
	v_cvt_pk_bf16_f32 v45, v48, v45
	global_store_dwordx4 v[46:47], v[42:45], off nt
	v_max_f32_e32 v37, v37, v37
	s_mov_b64 s[38:39], 0x240000
	v_mul_f32_e32 v42, v34, v34
	v_max_f32_e32 v34, v39, v39
	v_mul_f32_e32 v39, v35, v35
	v_max_f32_e32 v35, v40, v40
	v_mul_f32_e32 v40, v36, v36
	v_max_f32_e32 v36, v41, v41
	v_max_f32_e32 v35, 0, v35
	v_max_f32_e32 v36, 0, v36
	v_max_f32_e32 v38, v38, v38
	v_max_f32_e32 v34, 0, v34
	v_mul_f32_e32 v35, v35, v35
	v_max_f32_e32 v37, 0, v37
	v_mul_f32_e32 v36, v36, v36
	v_max_f32_e32 v26, v26, v26
	v_lshl_add_u64 v[50:51], v[140:141], 0, s[38:39]
	v_max_f32_e32 v38, 0, v38
	v_mul_f32_e32 v34, v34, v34
	v_mul_f32_e32 v37, v37, v37
	v_cvt_pk_bf16_f32 v35, v35, v36
	v_cvt_pk_bf16_f32 v36, v42, v39
	v_max_f32_e32 v26, 0, v26
	v_max_f32_e32 v27, v27, v27
	v_max_f32_e32 v28, v28, v28
	v_mul_f32_e32 v38, v38, v38
	v_cvt_pk_bf16_f32 v34, v38, v34
	v_cvt_pk_bf16_f32 v37, v40, v37
	global_store_dwordx4 v[50:51], v[34:37], off offset:256 nt
	v_max_f32_e32 v30, v30, v30
	v_max_f32_e32 v27, 0, v27
	v_mul_f32_e32 v36, v26, v26
	v_max_f32_e32 v26, v31, v31
	v_max_f32_e32 v28, 0, v28
	v_max_f32_e32 v30, 0, v30
	v_max_f32_e32 v26, 0, v26
	v_mul_f32_e32 v31, v27, v27
	v_max_f32_e32 v27, v32, v32
	v_mul_f32_e32 v32, v28, v28
	v_max_f32_e32 v28, v33, v33
	v_mul_f32_e32 v30, v30, v30
	v_mul_f32_e32 v26, v26, v26
	v_max_f32_e32 v27, 0, v27
	v_max_f32_e32 v28, 0, v28
	v_max_f32_e32 v29, v29, v29
	s_mov_b32 s8, 0x280000
	v_mul_f32_e32 v27, v27, v27
	v_max_f32_e32 v29, 0, v29
	v_mul_f32_e32 v28, v28, v28
	v_cvt_pk_bf16_f32 v26, v30, v26
	v_add_co_u32_e32 v30, vcc, s8, v140
	v_max_f32_e32 v18, v18, v18
	v_max_f32_e32 v19, v19, v19
	v_max_f32_e32 v20, v20, v20
	v_mul_f32_e32 v29, v29, v29
	v_cvt_pk_bf16_f32 v27, v27, v28
	v_cvt_pk_bf16_f32 v28, v36, v31
	v_addc_co_u32_e32 v31, vcc, 0, v141, vcc
	v_max_f32_e32 v18, 0, v18
	v_max_f32_e32 v19, 0, v19
	v_max_f32_e32 v20, 0, v20
	v_cvt_pk_bf16_f32 v29, v32, v29
	global_store_dwordx4 v[30:31], v[26:29], off nt
	v_max_f32_e32 v21, v21, v21
	s_mov_b64 s[38:39], 0x280000
	v_mul_f32_e32 v26, v18, v18
	v_max_f32_e32 v18, v23, v23
	v_mul_f32_e32 v23, v19, v19
	v_max_f32_e32 v19, v24, v24
	v_mul_f32_e32 v24, v20, v20
	v_max_f32_e32 v20, v25, v25
	v_max_f32_e32 v19, 0, v19
	v_max_f32_e32 v20, 0, v20
	v_max_f32_e32 v22, v22, v22
	v_max_f32_e32 v18, 0, v18
	v_mul_f32_e32 v19, v19, v19
	v_max_f32_e32 v21, 0, v21
	v_mul_f32_e32 v20, v20, v20
	v_max_f32_e32 v10, v10, v10
	v_lshl_add_u64 v[34:35], v[140:141], 0, s[38:39]
	v_max_f32_e32 v22, 0, v22
	v_mul_f32_e32 v18, v18, v18
	v_mul_f32_e32 v21, v21, v21
	v_cvt_pk_bf16_f32 v19, v19, v20
	v_cvt_pk_bf16_f32 v20, v26, v23
	v_max_f32_e32 v10, 0, v10
	v_max_f32_e32 v11, v11, v11
	v_max_f32_e32 v12, v12, v12
	v_mul_f32_e32 v22, v22, v22
	v_cvt_pk_bf16_f32 v18, v22, v18
	v_cvt_pk_bf16_f32 v21, v24, v21
	global_store_dwordx4 v[34:35], v[18:21], off offset:256 nt
	v_max_f32_e32 v14, v14, v14
	v_max_f32_e32 v11, 0, v11
	v_mul_f32_e32 v20, v10, v10
	v_max_f32_e32 v10, v15, v15
	v_max_f32_e32 v12, 0, v12
	v_max_f32_e32 v14, 0, v14
	v_max_f32_e32 v10, 0, v10
	v_mul_f32_e32 v15, v11, v11
	v_max_f32_e32 v11, v16, v16
	v_mul_f32_e32 v16, v12, v12
	v_max_f32_e32 v12, v17, v17
	v_mul_f32_e32 v14, v14, v14
	v_mul_f32_e32 v10, v10, v10
	v_max_f32_e32 v11, 0, v11
	v_max_f32_e32 v12, 0, v12
	v_max_f32_e32 v13, v13, v13
	s_mov_b32 s8, 0x2c0000
	v_mul_f32_e32 v11, v11, v11
	v_max_f32_e32 v13, 0, v13
	v_mul_f32_e32 v12, v12, v12
	v_cvt_pk_bf16_f32 v10, v14, v10
	v_add_co_u32_e32 v14, vcc, s8, v140
	v_max_f32_e32 v2, v2, v2
	v_max_f32_e32 v3, v3, v3
	v_max_f32_e32 v4, v4, v4
	v_mul_f32_e32 v13, v13, v13
	v_cvt_pk_bf16_f32 v11, v11, v12
	v_cvt_pk_bf16_f32 v12, v20, v15
	v_addc_co_u32_e32 v15, vcc, 0, v141, vcc
	v_max_f32_e32 v2, 0, v2
	v_max_f32_e32 v3, 0, v3
	v_max_f32_e32 v4, 0, v4
	v_cvt_pk_bf16_f32 v13, v16, v13
	global_store_dwordx4 v[14:15], v[10:13], off nt
	v_max_f32_e32 v5, v5, v5
	s_mov_b64 s[38:39], 0x2c0000
	v_mul_f32_e32 v10, v2, v2
	v_max_f32_e32 v2, v7, v7
	v_mul_f32_e32 v7, v3, v3
	v_max_f32_e32 v3, v8, v8
	v_mul_f32_e32 v8, v4, v4
	v_max_f32_e32 v4, v9, v9
	v_max_f32_e32 v6, v6, v6
	v_max_f32_e32 v2, 0, v2
	v_max_f32_e32 v3, 0, v3
	v_max_f32_e32 v4, 0, v4
	v_max_f32_e32 v5, 0, v5
	v_lshl_add_u64 v[18:19], v[140:141], 0, s[38:39]
	v_max_f32_e32 v6, 0, v6
	v_mul_f32_e32 v2, v2, v2
	v_mul_f32_e32 v3, v3, v3
	v_mul_f32_e32 v4, v4, v4
	v_mul_f32_e32 v5, v5, v5
	s_and_b64 vcc, exec, s[40:41]
	s_mov_b32 s68, s26
	s_mov_b32 s8, s28
	s_mov_b64 s[46:47], s[44:45]
	s_mov_b64 s[48:49], s[42:43]
	v_mul_f32_e32 v6, v6, v6
	v_cvt_pk_bf16_f32 v2, v6, v2
	v_cvt_pk_bf16_f32 v3, v3, v4
	v_cvt_pk_bf16_f32 v4, v10, v7
	v_cvt_pk_bf16_f32 v5, v8, v5
	global_store_dwordx4 v[18:19], v[2:5], off offset:256 nt
	s_cbranch_vccz .LBB0_70
	s_waitcnt vmcnt(0)
	s_cmpk_gt_u32 s52, 0xff
	s_cbranch_scc1 .LBB0_77
	s_barrier

; #define PG8_STAGE(bufoff, gbase, voff) do { _Pragma("unroll") for (int _i = 0; _i < 2; ++_i) \
;         __builtin_amdgcn_global_load_lds((const unsigned*)((const char*)(gbase) + (voff)[_i]), (LAS unsigned*)(lds + (bufoff) + ldsw + _i * 8192), 16, 0, 0); } while (0)
; #define PG8_LDA(dst, b, h) do { _Pragma("unroll") for (int m = 0; m < 4; ++m) _Pragma("unroll") for (int k = 0; k < 2; ++k) dst[m][k] = *(const LAS bf16x8*)(lds + PG8_SA(b, h) + aoff + m * 2048 + k * 1024); } while (0)
; #define PG8_LDB(dst, b, h) do { _Pragma("unroll") for (int n = 0; n < 2; ++n) _Pragma("unroll") for (int k = 0; k < 2; ++k) dst[n][k] = *(const LAS bf16x8*)(lds + PG8_SB(b, h) + boff + n * 2048 + k * 1024); } while (0)
; #define PG8_MMA(ai, bj, At, Bt) do { __builtin_amdgcn_s_setprio(1); _Pragma("unroll") for (int m = 0; m < 4; ++m) _Pragma("unroll") for (int n = 0; n < 2; ++n) _Pragma("unroll") for (int k = 0; k < 2; ++k) \
;         acc[ai][bj][m][n] = __builtin_amdgcn_mfma_f32_16x16x32_bf16(Bt[n][k], At[m][k], acc[ai][bj][m][n], 0, 0, 0); __builtin_amdgcn_s_setprio(0); } while (0)
; #define PG8_BAR __builtin_amdgcn_s_barrier()
; template <class Epi, class Sched>
; __device__ __forceinline__ void gemm_phase(LAS unsigned char* lds, const Gemm g, const Sched& S, const Epi& E) {
;     ...
;         const bool has_next = S.next(ui + 1, nxt);
;         const char* nA = has_next ? (const char*)g.A + (size_t)nxt.pm * tstep + (size_t)nxt.ks * sstep : cA; const char* nB = has_next ? (const char*)g.Bt + (size_t)nxt.pn * tstep + (size_t)nxt.ks * sstep : cB;
;         for (int t = 0; t < nt; t += 2) {
;             const bool last = (t == nt - 2);
;             const char* a1 = cA + (size_t)(t + 1) * kstep;
;             const char* a2 = last ? nA : cA + (size_t)(t + 2) * kstep; const char* b2 = last ? nB : cB + (size_t)(t + 2) * kstep;
;             const char* a3 = a2 + kstep; const char* b3 = b2 + kstep;
;             PG8_LDB(B0, 0, 0); PG8_SCHED; PG8_LDA(At, 0, 0); PG8_STAGE(PG8_SA(1, 1), a1 + hstep, voffA);
;             PG8_WAIT_L(8); PG8_BAR; PG8_WAIT_L(0); PG8_MMA(0, 0, At, B0); PG8_BAR; PG8_SCHED;
;     ...
; #pragma unroll
;         for (int a = 0; a < 2; ++a)
; #pragma unroll
;             for (int b = 0; b < 2; ++b)
; #pragma unroll
;                 for (int m = 0; m < 4; ++m)
; #pragma unroll
;                     for (int n = 0; n < 2; ++n) acc[a][b][m][n] = (f32x4){0.f, 0.f, 0.f, 0.f};
.LBB0_353:
	s_ashr_i32 s9, s8, 31
	s_xor_b64 s[46:47], s[54:55], -1
	s_lshl_b64 s[44:45], s[8:9], 20
	s_add_u32 s44, s26, s44
	s_addc_u32 s45, s27, s45
	s_and_b64 s[48:49], s[54:55], exec
	s_cselect_b32 s9, s45, s53
	s_cselect_b32 s66, s44, s52
	s_ashr_i32 s43, s42, 31
	s_lshl_b64 s[48:49], s[42:43], 20
	s_add_u32 s48, s75, s48
	s_addc_u32 s49, s76, s49
	s_and_b64 s[54:55], s[54:55], exec
	s_cselect_b32 s43, s49, s51
	s_cselect_b32 s67, s48, s50
	s_add_u32 s68, s50, 0x100
	s_addc_u32 s69, s51, 0
	s_add_u32 s50, s52, 0x80080
	v_mov_b32_e32 v2, 0
	s_addc_u32 s51, s53, 0
	s_mov_b32 s70, -2
	v_mov_b32_e32 v3, v2
	v_mov_b32_e32 v4, v2
	v_mov_b32_e32 v5, v2
	v_mov_b32_e32 v6, v2
	v_mov_b32_e32 v7, v2
	v_mov_b32_e32 v8, v2
	v_mov_b32_e32 v9, v2
	v_mov_b32_e32 v10, v2
	v_mov_b32_e32 v11, v2
	v_mov_b32_e32 v12, v2
	v_mov_b32_e32 v13, v2
	v_mov_b32_e32 v18, v2
	v_mov_b32_e32 v19, v2
	v_mov_b32_e32 v20, v2
	v_mov_b32_e32 v21, v2
	v_mov_b32_e32 v26, v2
	v_mov_b32_e32 v27, v2
	v_mov_b32_e32 v28, v2
	v_mov_b32_e32 v29, v2
	v_mov_b32_e32 v34, v2
	v_mov_b32_e32 v35, v2
	v_mov_b32_e32 v36, v2
	v_mov_b32_e32 v37, v2
	v_mov_b32_e32 v42, v2
	v_mov_b32_e32 v43, v2
	v_mov_b32_e32 v44, v2
	v_mov_b32_e32 v45, v2
	v_mov_b32_e32 v50, v2
	v_mov_b32_e32 v51, v2
	v_mov_b32_e32 v52, v2
	v_mov_b32_e32 v53, v2
	v_mov_b32_e32 v14, v2
	v_mov_b32_e32 v15, v2
	v_mov_b32_e32 v16, v2
	v_mov_b32_e32 v17, v2
	v_mov_b32_e32 v22, v2
	v_mov_b32_e32 v23, v2
	v_mov_b32_e32 v24, v2
	v_mov_b32_e32 v25, v2
	v_mov_b32_e32 v30, v2
	v_mov_b32_e32 v31, v2
	v_mov_b32_e32 v32, v2
	v_mov_b32_e32 v33, v2
	v_mov_b32_e32 v38, v2
	v_mov_b32_e32 v39, v2
	v_mov_b32_e32 v40, v2
	v_mov_b32_e32 v41, v2
	v_mov_b32_e32 v46, v2
	v_mov_b32_e32 v47, v2
	v_mov_b32_e32 v48, v2
	v_mov_b32_e32 v49, v2
	v_mov_b32_e32 v54, v2
	v_mov_b32_e32 v55, v2
	v_mov_b32_e32 v56, v2
	v_mov_b32_e32 v57, v2
	v_mov_b32_e32 v58, v2
	v_mov_b32_e32 v59, v2
	v_mov_b32_e32 v60, v2
	v_mov_b32_e32 v61, v2
	v_mov_b32_e32 v62, v2
	v_mov_b32_e32 v63, v2
	v_mov_b32_e32 v64, v2
	v_mov_b32_e32 v65, v2
	v_mov_b32_e32 v66, v2
	v_mov_b32_e32 v67, v2
	v_mov_b32_e32 v68, v2
	v_mov_b32_e32 v69, v2
	v_mov_b32_e32 v70, v2
	v_mov_b32_e32 v71, v2
	v_mov_b32_e32 v72, v2
	v_mov_b32_e32 v73, v2
	v_mov_b32_e32 v74, v2
	v_mov_b32_e32 v75, v2
	v_mov_b32_e32 v76, v2
	v_mov_b32_e32 v77, v2
	v_mov_b32_e32 v82, v2
	v_mov_b32_e32 v83, v2
	v_mov_b32_e32 v84, v2
	v_mov_b32_e32 v85, v2
	v_mov_b32_e32 v90, v2
	v_mov_b32_e32 v91, v2
	v_mov_b32_e32 v92, v2
	v_mov_b32_e32 v93, v2
	v_mov_b32_e32 v98, v2
	v_mov_b32_e32 v99, v2
	v_mov_b32_e32 v100, v2
	v_mov_b32_e32 v101, v2
	v_mov_b32_e32 v106, v2
	v_mov_b32_e32 v107, v2
	v_mov_b32_e32 v108, v2
	v_mov_b32_e32 v109, v2
	v_mov_b32_e32 v114, v2
	v_mov_b32_e32 v115, v2
	v_mov_b32_e32 v116, v2
	v_mov_b32_e32 v117, v2
	v_mov_b32_e32 v78, v2
	v_mov_b32_e32 v79, v2
	v_mov_b32_e32 v80, v2
	v_mov_b32_e32 v81, v2
	v_mov_b32_e32 v86, v2
	v_mov_b32_e32 v87, v2
	v_mov_b32_e32 v88, v2
	v_mov_b32_e32 v89, v2
	v_mov_b32_e32 v94, v2
	v_mov_b32_e32 v95, v2
	v_mov_b32_e32 v96, v2
	v_mov_b32_e32 v97, v2
	v_mov_b32_e32 v102, v2
	v_mov_b32_e32 v103, v2
	v_mov_b32_e32 v104, v2
	v_mov_b32_e32 v105, v2
	v_mov_b32_e32 v110, v2
	v_mov_b32_e32 v111, v2
	v_mov_b32_e32 v112, v2
	v_mov_b32_e32 v113, v2
	v_mov_b32_e32 v118, v2
	v_mov_b32_e32 v119, v2
	v_mov_b32_e32 v120, v2
	v_mov_b32_e32 v121, v2
	v_mov_b32_e32 v122, v2
	v_mov_b32_e32 v123, v2
	v_mov_b32_e32 v124, v2
	v_mov_b32_e32 v125, v2
	v_mov_b32_e32 v126, v2
	v_mov_b32_e32 v127, v2
	v_mov_b32_e32 v128, v2
	v_mov_b32_e32 v129, v2
	s_cmpk_gt_u32 s25, 0xff
	s_cbranch_scc0 .Ldsx1_354
	s_cmp_eq_u32 s64, 1
	s_cbranch_scc1 .Ldsx1_354
	s_barrier
.Ldsx1_354:
.LBB0_354:
	s_add_u32 s38, s50, 0xfff80080
	s_addc_u32 s39, s51, -1
	s_cmp_eq_u32 s70, 28
	s_cselect_b32 s55, s9, s39
	s_cselect_b32 s54, s66, s38
	s_cselect_b32 s53, s43, s69
	s_cselect_b32 s52, s67, s68
	s_add_i32 m0, s29, 0xc000
	s_nop 0
	global_load_lds_dwordx4 v138, s[50:51]
	s_add_i32 m0, s29, 0xe000
	s_nop 0
	global_load_lds_dwordx4 v136, s[50:51]
	s_add_i32 s71, 0, 0x10000
	ds_read_b128 v[140:143], v226
	ds_read_b128 v[148:151], v226 offset:1024
	ds_read_b128 v[152:155], v226 offset:2048
	ds_read_b128 v[160:163], v226 offset:3072
	ds_read_b128 v[164:167], v147
	ds_read_b128 v[168:171], v147 offset:1024
	ds_read_b128 v[172:175], v147 offset:2048
	ds_read_b128 v[176:179], v147 offset:3072
	ds_read_b128 v[180:183], v147 offset:4096
	ds_read_b128 v[184:187], v147 offset:5120
	ds_read_b128 v[188:191], v147 offset:6144
	ds_read_b128 v[192:195], v147 offset:7168
	s_add_i32 s38, 0, 0x14000
	ds_read_b128 v[196:199], v226 offset:16384
	ds_read_b128 v[200:203], v226 offset:17408
	ds_read_b128 v[204:207], v226 offset:18432
	ds_read_b128 v[210:213], v226 offset:19456
	s_waitcnt lgkmcnt(4)
	s_barrier
; #define PG8_STAGE(bufoff, gbase, voff) do { _Pragma("unroll") for (int _i = 0; _i < 2; ++_i) \
;         __builtin_amdgcn_global_load_lds((const unsigned*)((const char*)(gbase) + (voff)[_i]), (LAS unsigned*)(lds + (bufoff) + ldsw + _i * 8192), 16, 0, 0); } while (0)
; #define PG8_LDA(dst, b, h) do { _Pragma("unroll") for (int m = 0; m < 4; ++m) _Pragma("unroll") for (int k = 0; k < 2; ++k) dst[m][k] = *(const LAS bf16x8*)(lds + PG8_SA(b, h) + aoff + m * 2048 + k * 1024); } while (0)
; #define PG8_LDB(dst, b, h) do { _Pragma("unroll") for (int n = 0; n < 2; ++n) _Pragma("unroll") for (int k = 0; k < 2; ++k) dst[n][k] = *(const LAS bf16x8*)(lds + PG8_SB(b, h) + boff + n * 2048 + k * 1024); } while (0)
; #define PG8_MMA(ai, bj, At, Bt) do { __builtin_amdgcn_s_setprio(1); _Pragma("unroll") for (int m = 0; m < 4; ++m) _Pragma("unroll") for (int n = 0; n < 2; ++n) _Pragma("unroll") for (int k = 0; k < 2; ++k) \
;         acc[ai][bj][m][n] = __builtin_amdgcn_mfma_f32_16x16x32_bf16(Bt[n][k], At[m][k], acc[ai][bj][m][n], 0, 0, 0); __builtin_amdgcn_s_setprio(0); } while (0)
; #define PG8_WAIT_V(n) asm volatile("s_waitcnt vmcnt(" #n ")" ::: "memory")
; #define PG8_WAIT_L(n) asm volatile("s_waitcnt lgkmcnt(" #n ")" ::: "memory")
; #define PG8_BAR __builtin_amdgcn_s_barrier()
; #define PG8_SCHED __builtin_amdgcn_sched_barrier(0)
; template <class Epi, class Sched>
; __device__ __forceinline__ void gemm_phase(LAS unsigned char* lds, const Gemm g, const Sched& S, const Epi& E) {
;     ...
;             PG8_LDB(B0, 0, 0); PG8_SCHED; PG8_LDA(At, 0, 0); PG8_STAGE(PG8_SA(1, 1), a1 + hstep, voffA);
;             PG8_WAIT_L(8); PG8_BAR; PG8_WAIT_L(0); PG8_MMA(0, 0, At, B0); PG8_BAR; PG8_SCHED;
;             PG8_LDB(B1, 0, 1); PG8_STAGE(PG8_SB(0, 0), b2, voffB);
;             PG8_BAR; PG8_WAIT_L(0); PG8_MMA(0, 1, At, B1); PG8_BAR;
;             PG8_LDA(At, 0, 1); PG8_STAGE(PG8_SA(0, 0), a2, voffA);
;             PG8_BAR; PG8_WAIT_L(0); PG8_MMA(1, 0, At, B0); PG8_BAR; PG8_SCHED;
;             PG8_STAGE(PG8_SB(0, 1), b2 + hstep, voffB);
;             PG8_WAIT_V(6); PG8_BAR; PG8_MMA(1, 1, At, B1); PG8_BAR;
	s_waitcnt lgkmcnt(0)
	v_mfma_f32_16x16x32_bf16 v[126:129], v[140:143], v[164:167], v[126:129]
	v_mfma_f32_16x16x32_bf16 v[122:125], v[152:155], v[164:167], v[122:125]
	v_mfma_f32_16x16x32_bf16 v[118:121], v[140:143], v[172:175], v[118:121]
	v_mfma_f32_16x16x32_bf16 v[110:113], v[152:155], v[172:175], v[110:113]
	v_mfma_f32_16x16x32_bf16 v[102:105], v[140:143], v[180:183], v[102:105]
	v_mfma_f32_16x16x32_bf16 v[94:97], v[152:155], v[180:183], v[94:97]
	v_mfma_f32_16x16x32_bf16 v[86:89], v[140:143], v[188:191], v[86:89]
	v_mfma_f32_16x16x32_bf16 v[78:81], v[152:155], v[188:191], v[78:81]
	v_mfma_f32_16x16x32_bf16 v[126:129], v[148:151], v[168:171], v[126:129]
	v_mfma_f32_16x16x32_bf16 v[122:125], v[160:163], v[168:171], v[122:125]
	v_mfma_f32_16x16x32_bf16 v[118:121], v[148:151], v[176:179], v[118:121]
	v_mfma_f32_16x16x32_bf16 v[110:113], v[160:163], v[176:179], v[110:113]
	v_mfma_f32_16x16x32_bf16 v[102:105], v[148:151], v[184:187], v[102:105]
	v_mfma_f32_16x16x32_bf16 v[94:97], v[160:163], v[184:187], v[94:97]
	v_mfma_f32_16x16x32_bf16 v[86:89], v[148:151], v[192:195], v[86:89]
	v_mfma_f32_16x16x32_bf16 v[78:81], v[160:163], v[192:195], v[78:81]
	v_mfma_f32_16x16x32_bf16 v[114:117], v[196:199], v[164:167], v[114:117]
	v_mfma_f32_16x16x32_bf16 v[106:109], v[204:207], v[164:167], v[106:109]
	v_mfma_f32_16x16x32_bf16 v[98:101], v[196:199], v[172:175], v[98:101]
	v_mfma_f32_16x16x32_bf16 v[90:93], v[204:207], v[172:175], v[90:93]
	v_mfma_f32_16x16x32_bf16 v[82:85], v[196:199], v[180:183], v[82:85]
	v_mfma_f32_16x16x32_bf16 v[74:77], v[204:207], v[180:183], v[74:77]
	v_mfma_f32_16x16x32_bf16 v[70:73], v[196:199], v[188:191], v[70:73]
	v_mfma_f32_16x16x32_bf16 v[66:69], v[204:207], v[188:191], v[66:69]
	v_mfma_f32_16x16x32_bf16 v[114:117], v[200:203], v[168:171], v[114:117]
	v_mfma_f32_16x16x32_bf16 v[106:109], v[210:213], v[168:171], v[106:109]
	v_mfma_f32_16x16x32_bf16 v[98:101], v[200:203], v[176:179], v[98:101]
	v_mfma_f32_16x16x32_bf16 v[90:93], v[210:213], v[176:179], v[90:93]
	v_mfma_f32_16x16x32_bf16 v[82:85], v[200:203], v[184:187], v[82:85]
	v_mfma_f32_16x16x32_bf16 v[74:77], v[210:213], v[184:187], v[74:77]
	v_mfma_f32_16x16x32_bf16 v[70:73], v[200:203], v[192:195], v[70:73]
	v_mfma_f32_16x16x32_bf16 v[66:69], v[210:213], v[192:195], v[66:69]
	s_barrier
	s_add_i32 s39, s71, s56
	s_mov_b32 m0, s39
	s_nop 0
	global_load_lds_dwordx4 v0, s[52:53]
	s_add_i32 m0, s39, 0x2000
	s_nop 0
	global_load_lds_dwordx4 v134, s[52:53]
	s_mov_b32 m0, s29
	s_nop 0
	global_load_lds_dwordx4 v130, s[54:55]
	s_mov_b32 m0, s41
	s_nop 0
	global_load_lds_dwordx4 v132, s[54:55]
	ds_read_b128 v[164:167], v147 offset:16384
	ds_read_b128 v[168:171], v147 offset:17408
	ds_read_b128 v[172:175], v147 offset:18432
	ds_read_b128 v[176:179], v147 offset:19456
	ds_read_b128 v[180:183], v147 offset:20480
	ds_read_b128 v[184:187], v147 offset:21504
	ds_read_b128 v[188:191], v147 offset:22528
	ds_read_b128 v[192:195], v147 offset:23552
	s_waitcnt vmcnt(4)
	s_waitcnt lgkmcnt(0)
	s_barrier
	v_mfma_f32_16x16x32_bf16 v[62:65], v[140:143], v[164:167], v[62:65]
	v_mfma_f32_16x16x32_bf16 v[58:61], v[152:155], v[164:167], v[58:61]
	v_mfma_f32_16x16x32_bf16 v[54:57], v[140:143], v[172:175], v[54:57]
	v_mfma_f32_16x16x32_bf16 v[46:49], v[152:155], v[172:175], v[46:49]
	v_mfma_f32_16x16x32_bf16 v[38:41], v[140:143], v[180:183], v[38:41]
	v_mfma_f32_16x16x32_bf16 v[30:33], v[152:155], v[180:183], v[30:33]
	v_mfma_f32_16x16x32_bf16 v[22:25], v[140:143], v[188:191], v[22:25]
	v_mfma_f32_16x16x32_bf16 v[14:17], v[152:155], v[188:191], v[14:17]
	v_mfma_f32_16x16x32_bf16 v[62:65], v[148:151], v[168:171], v[62:65]
	v_mfma_f32_16x16x32_bf16 v[58:61], v[160:163], v[168:171], v[58:61]
	v_mfma_f32_16x16x32_bf16 v[54:57], v[148:151], v[176:179], v[54:57]
	v_mfma_f32_16x16x32_bf16 v[46:49], v[160:163], v[176:179], v[46:49]
	v_mfma_f32_16x16x32_bf16 v[38:41], v[148:151], v[184:187], v[38:41]
	v_mfma_f32_16x16x32_bf16 v[30:33], v[160:163], v[184:187], v[30:33]
	v_mfma_f32_16x16x32_bf16 v[22:25], v[148:151], v[192:195], v[22:25]
	v_mfma_f32_16x16x32_bf16 v[14:17], v[160:163], v[192:195], v[14:17]
	v_mfma_f32_16x16x32_bf16 v[50:53], v[196:199], v[164:167], v[50:53]
	v_mfma_f32_16x16x32_bf16 v[42:45], v[204:207], v[164:167], v[42:45]
	v_mfma_f32_16x16x32_bf16 v[34:37], v[196:199], v[172:175], v[34:37]
	v_mfma_f32_16x16x32_bf16 v[26:29], v[204:207], v[172:175], v[26:29]
	v_mfma_f32_16x16x32_bf16 v[18:21], v[196:199], v[180:183], v[18:21]
	v_mfma_f32_16x16x32_bf16 v[10:13], v[204:207], v[180:183], v[10:13]
	v_mfma_f32_16x16x32_bf16 v[6:9], v[196:199], v[188:191], v[6:9]
	v_mfma_f32_16x16x32_bf16 v[2:5], v[204:207], v[188:191], v[2:5]
	v_mfma_f32_16x16x32_bf16 v[50:53], v[200:203], v[168:171], v[50:53]
	v_mfma_f32_16x16x32_bf16 v[42:45], v[210:213], v[168:171], v[42:45]
	v_mfma_f32_16x16x32_bf16 v[34:37], v[200:203], v[176:179], v[34:37]
	v_mfma_f32_16x16x32_bf16 v[26:29], v[210:213], v[176:179], v[26:29]
	v_mfma_f32_16x16x32_bf16 v[18:21], v[200:203], v[184:187], v[18:21]
	v_mfma_f32_16x16x32_bf16 v[10:13], v[210:213], v[184:187], v[10:13]
	v_mfma_f32_16x16x32_bf16 v[6:9], v[200:203], v[192:195], v[6:9]
	v_mfma_f32_16x16x32_bf16 v[2:5], v[210:213], v[192:195], v[2:5]
	s_barrier
; #define PG8_STAGE(bufoff, gbase, voff) do { _Pragma("unroll") for (int _i = 0; _i < 2; ++_i) \
;         __builtin_amdgcn_global_load_lds((const unsigned*)((const char*)(gbase) + (voff)[_i]), (LAS unsigned*)(lds + (bufoff) + ldsw + _i * 8192), 16, 0, 0); } while (0)
; #define PG8_LDA(dst, b, h) do { _Pragma("unroll") for (int m = 0; m < 4; ++m) _Pragma("unroll") for (int k = 0; k < 2; ++k) dst[m][k] = *(const LAS bf16x8*)(lds + PG8_SA(b, h) + aoff + m * 2048 + k * 1024); } while (0)
; #define PG8_LDB(dst, b, h) do { _Pragma("unroll") for (int n = 0; n < 2; ++n) _Pragma("unroll") for (int k = 0; k < 2; ++k) dst[n][k] = *(const LAS bf16x8*)(lds + PG8_SB(b, h) + boff + n * 2048 + k * 1024); } while (0)
; #define PG8_MMA(ai, bj, At, Bt) do { __builtin_amdgcn_s_setprio(1); _Pragma("unroll") for (int m = 0; m < 4; ++m) _Pragma("unroll") for (int n = 0; n < 2; ++n) _Pragma("unroll") for (int k = 0; k < 2; ++k) \
;         acc[ai][bj][m][n] = __builtin_amdgcn_mfma_f32_16x16x32_bf16(Bt[n][k], At[m][k], acc[ai][bj][m][n], 0, 0, 0); __builtin_amdgcn_s_setprio(0); } while (0)
; #define PG8_WAIT_L(n) asm volatile("s_waitcnt lgkmcnt(" #n ")" ::: "memory")
; #define PG8_BAR __builtin_amdgcn_s_barrier()
; #define PG8_SCHED __builtin_amdgcn_sched_barrier(0)
; template <class Epi, class Sched>
; __device__ __forceinline__ void gemm_phase(LAS unsigned char* lds, const Gemm g, const Sched& S, const Epi& E) {
;     ...
;             PG8_LDB(B0, 1, 0); PG8_SCHED; PG8_LDA(At, 1, 0); PG8_STAGE(PG8_SA(0, 1), a2 + hstep, voffA);
;             PG8_WAIT_L(8); PG8_BAR; PG8_WAIT_L(0); PG8_MMA(0, 0, At, B0); PG8_BAR; PG8_SCHED;
;             PG8_LDB(B1, 1, 1); PG8_STAGE(PG8_SB(1, 0), b3, voffB);
;             PG8_BAR; PG8_WAIT_L(0); PG8_MMA(0, 1, At, B1); PG8_BAR;
;             PG8_LDA(At, 1, 1); PG8_STAGE(PG8_SA(1, 0), a3, voffA);
;             PG8_BAR; PG8_WAIT_L(0); PG8_MMA(1, 0, At, B0); PG8_BAR; PG8_SCHED;
	s_add_u32 s72, s52, 0x80000
	s_addc_u32 s73, s53, 0
	s_add_i32 s38, s38, s56
	s_mov_b32 m0, s38
	s_nop 0
	global_load_lds_dwordx4 v0, s[72:73]
	s_add_i32 m0, s38, 0x2000
	s_nop 0
	global_load_lds_dwordx4 v134, s[72:73]
	s_add_u32 s54, s54, 0x80000
	s_addc_u32 s55, s55, 0
	s_mov_b32 m0, s57
	s_nop 0
	global_load_lds_dwordx4 v130, s[54:55]
	s_mov_b32 m0, s58
	s_nop 0
	global_load_lds_dwordx4 v132, s[54:55]
	s_add_i32 s38, 0, 0x18000
	ds_read_b128 v[140:143], v226 offset:32768
	ds_read_b128 v[148:151], v226 offset:33792
	ds_read_b128 v[152:155], v226 offset:34816
	ds_read_b128 v[160:163], v226 offset:35840
	ds_read_b128 v[164:167], v147 offset:32768
	ds_read_b128 v[168:171], v147 offset:33792
	ds_read_b128 v[172:175], v147 offset:34816
	ds_read_b128 v[176:179], v147 offset:35840
	ds_read_b128 v[180:183], v147 offset:36864
	ds_read_b128 v[184:187], v147 offset:37888
	ds_read_b128 v[188:191], v147 offset:38912
	ds_read_b128 v[192:195], v147 offset:39936
	s_add_i32 s39, 0, 0x1c000
	ds_read_b128 v[196:199], v226 offset:49152
	ds_read_b128 v[200:203], v226 offset:50176
	ds_read_b128 v[204:207], v226 offset:51200
	ds_read_b128 v[210:213], v226 offset:52224
	s_waitcnt lgkmcnt(4)
	s_barrier
	s_waitcnt lgkmcnt(0)
	v_mfma_f32_16x16x32_bf16 v[126:129], v[140:143], v[164:167], v[126:129]
	v_mfma_f32_16x16x32_bf16 v[122:125], v[152:155], v[164:167], v[122:125]
	v_mfma_f32_16x16x32_bf16 v[118:121], v[140:143], v[172:175], v[118:121]
	v_mfma_f32_16x16x32_bf16 v[110:113], v[152:155], v[172:175], v[110:113]
	v_mfma_f32_16x16x32_bf16 v[102:105], v[140:143], v[180:183], v[102:105]
	v_mfma_f32_16x16x32_bf16 v[94:97], v[152:155], v[180:183], v[94:97]
	v_mfma_f32_16x16x32_bf16 v[86:89], v[140:143], v[188:191], v[86:89]
	v_mfma_f32_16x16x32_bf16 v[78:81], v[152:155], v[188:191], v[78:81]
	v_mfma_f32_16x16x32_bf16 v[126:129], v[148:151], v[168:171], v[126:129]
	v_mfma_f32_16x16x32_bf16 v[122:125], v[160:163], v[168:171], v[122:125]
	v_mfma_f32_16x16x32_bf16 v[118:121], v[148:151], v[176:179], v[118:121]
	v_mfma_f32_16x16x32_bf16 v[110:113], v[160:163], v[176:179], v[110:113]
	v_mfma_f32_16x16x32_bf16 v[102:105], v[148:151], v[184:187], v[102:105]
	v_mfma_f32_16x16x32_bf16 v[94:97], v[160:163], v[184:187], v[94:97]
	v_mfma_f32_16x16x32_bf16 v[86:89], v[148:151], v[192:195], v[86:89]
	v_mfma_f32_16x16x32_bf16 v[78:81], v[160:163], v[192:195], v[78:81]
	v_mfma_f32_16x16x32_bf16 v[114:117], v[196:199], v[164:167], v[114:117]
	v_mfma_f32_16x16x32_bf16 v[106:109], v[204:207], v[164:167], v[106:109]
	v_mfma_f32_16x16x32_bf16 v[98:101], v[196:199], v[172:175], v[98:101]
	v_mfma_f32_16x16x32_bf16 v[90:93], v[204:207], v[172:175], v[90:93]
	v_mfma_f32_16x16x32_bf16 v[82:85], v[196:199], v[180:183], v[82:85]
	v_mfma_f32_16x16x32_bf16 v[74:77], v[204:207], v[180:183], v[74:77]
	v_mfma_f32_16x16x32_bf16 v[70:73], v[196:199], v[188:191], v[70:73]
	v_mfma_f32_16x16x32_bf16 v[66:69], v[204:207], v[188:191], v[66:69]
	v_mfma_f32_16x16x32_bf16 v[114:117], v[200:203], v[168:171], v[114:117]
	v_mfma_f32_16x16x32_bf16 v[106:109], v[210:213], v[168:171], v[106:109]
	v_mfma_f32_16x16x32_bf16 v[98:101], v[200:203], v[176:179], v[98:101]
	v_mfma_f32_16x16x32_bf16 v[90:93], v[210:213], v[176:179], v[90:93]
	v_mfma_f32_16x16x32_bf16 v[82:85], v[200:203], v[184:187], v[82:85]
	v_mfma_f32_16x16x32_bf16 v[74:77], v[210:213], v[184:187], v[74:77]
	v_mfma_f32_16x16x32_bf16 v[70:73], v[200:203], v[192:195], v[70:73]
	v_mfma_f32_16x16x32_bf16 v[66:69], v[210:213], v[192:195], v[66:69]
	s_barrier
	s_add_i32 s38, s38, s56
	s_add_u32 s100, s52, s36
	s_addc_u32 s101, s53, s37
	s_mov_b32 m0, s38
	s_nop 0
	global_load_lds_dwordx4 v0, s[100:101]
	s_add_i32 m0, s38, 0x2000
	s_nop 0
	global_load_lds_dwordx4 v134, s[100:101]
	s_mov_b32 m0, s59
	s_add_u32 s100, s54, s36
	s_addc_u32 s101, s55, s37
	s_sub_u32 s100, s100, 0x80000
	s_subb_u32 s101, s101, 0
	global_load_lds_dwordx4 v130, s[100:101]
	s_mov_b32 m0, s60
	s_nop 0
	global_load_lds_dwordx4 v132, s[100:101]
	ds_read_b128 v[164:167], v147 offset:49152
	ds_read_b128 v[168:171], v147 offset:50176
	ds_read_b128 v[172:175], v147 offset:51200
	ds_read_b128 v[176:179], v147 offset:52224
	ds_read_b128 v[180:183], v147 offset:53248
	ds_read_b128 v[184:187], v147 offset:54272
	ds_read_b128 v[188:191], v147 offset:55296
	ds_read_b128 v[192:195], v147 offset:56320
	s_waitcnt vmcnt(4)
	s_waitcnt lgkmcnt(0)
	s_barrier
; #define PG8_STAGE(bufoff, gbase, voff) do { _Pragma("unroll") for (int _i = 0; _i < 2; ++_i) \
;         __builtin_amdgcn_global_load_lds((const unsigned*)((const char*)(gbase) + (voff)[_i]), (LAS unsigned*)(lds + (bufoff) + ldsw + _i * 8192), 16, 0, 0); } while (0)
; #define PG8_MMA(ai, bj, At, Bt) do { __builtin_amdgcn_s_setprio(1); _Pragma("unroll") for (int m = 0; m < 4; ++m) _Pragma("unroll") for (int n = 0; n < 2; ++n) _Pragma("unroll") for (int k = 0; k < 2; ++k) \
;         acc[ai][bj][m][n] = __builtin_amdgcn_mfma_f32_16x16x32_bf16(Bt[n][k], At[m][k], acc[ai][bj][m][n], 0, 0, 0); __builtin_amdgcn_s_setprio(0); } while (0)
; #define PG8_WAIT_V(n) asm volatile("s_waitcnt vmcnt(" #n ")" ::: "memory")
; #define PG8_WAIT_L(n) asm volatile("s_waitcnt lgkmcnt(" #n ")" ::: "memory")
; #define PG8_BAR __builtin_amdgcn_s_barrier()
; #define PG8_SCHED __builtin_amdgcn_sched_barrier(0)
; template <class Epi, class Sched>
; __device__ __forceinline__ void gemm_phase(LAS unsigned char* lds, const Gemm g, const Sched& S, const Epi& E) {
;     ...
;             PG8_BAR; PG8_WAIT_L(0); PG8_MMA(1, 0, At, B0); PG8_BAR; PG8_SCHED;
;             PG8_STAGE(PG8_SB(1, 1), b3 + hstep, voffB);
;             PG8_WAIT_V(6); PG8_BAR; PG8_MMA(1, 1, At, B1); PG8_BAR;
	v_mfma_f32_16x16x32_bf16 v[62:65], v[140:143], v[164:167], v[62:65]
	v_mfma_f32_16x16x32_bf16 v[58:61], v[152:155], v[164:167], v[58:61]
	v_mfma_f32_16x16x32_bf16 v[54:57], v[140:143], v[172:175], v[54:57]
	v_mfma_f32_16x16x32_bf16 v[46:49], v[152:155], v[172:175], v[46:49]
	v_mfma_f32_16x16x32_bf16 v[38:41], v[140:143], v[180:183], v[38:41]
	v_mfma_f32_16x16x32_bf16 v[30:33], v[152:155], v[180:183], v[30:33]
	v_mfma_f32_16x16x32_bf16 v[22:25], v[140:143], v[188:191], v[22:25]
	v_mfma_f32_16x16x32_bf16 v[14:17], v[152:155], v[188:191], v[14:17]
	v_mfma_f32_16x16x32_bf16 v[62:65], v[148:151], v[168:171], v[62:65]
	v_mfma_f32_16x16x32_bf16 v[58:61], v[160:163], v[168:171], v[58:61]
	v_mfma_f32_16x16x32_bf16 v[54:57], v[148:151], v[176:179], v[54:57]
	v_mfma_f32_16x16x32_bf16 v[46:49], v[160:163], v[176:179], v[46:49]
	v_mfma_f32_16x16x32_bf16 v[38:41], v[148:151], v[184:187], v[38:41]
	v_mfma_f32_16x16x32_bf16 v[30:33], v[160:163], v[184:187], v[30:33]
	v_mfma_f32_16x16x32_bf16 v[22:25], v[148:151], v[192:195], v[22:25]
	v_mfma_f32_16x16x32_bf16 v[14:17], v[160:163], v[192:195], v[14:17]
	s_add_u32 s52, s52, 0x80080
	s_addc_u32 s53, s53, 0
	s_add_i32 s38, s39, s56
	s_mov_b32 m0, s38
	s_nop 0
	global_load_lds_dwordx4 v0, s[52:53]
	s_add_i32 m0, s38, 0x2000
	s_nop 0
	global_load_lds_dwordx4 v134, s[52:53]
	v_mfma_f32_16x16x32_bf16 v[50:53], v[196:199], v[164:167], v[50:53]
	v_mfma_f32_16x16x32_bf16 v[42:45], v[204:207], v[164:167], v[42:45]
	v_mfma_f32_16x16x32_bf16 v[34:37], v[196:199], v[172:175], v[34:37]
	v_mfma_f32_16x16x32_bf16 v[26:29], v[204:207], v[172:175], v[26:29]
	v_mfma_f32_16x16x32_bf16 v[18:21], v[196:199], v[180:183], v[18:21]
	v_mfma_f32_16x16x32_bf16 v[10:13], v[204:207], v[180:183], v[10:13]
	v_mfma_f32_16x16x32_bf16 v[6:9], v[196:199], v[188:191], v[6:9]
	v_mfma_f32_16x16x32_bf16 v[2:5], v[204:207], v[188:191], v[2:5]
	v_mfma_f32_16x16x32_bf16 v[50:53], v[200:203], v[168:171], v[50:53]
	v_mfma_f32_16x16x32_bf16 v[42:45], v[210:213], v[168:171], v[42:45]
	v_mfma_f32_16x16x32_bf16 v[34:37], v[200:203], v[176:179], v[34:37]
	v_mfma_f32_16x16x32_bf16 v[26:29], v[210:213], v[176:179], v[26:29]
	v_mfma_f32_16x16x32_bf16 v[18:21], v[200:203], v[184:187], v[18:21]
	v_mfma_f32_16x16x32_bf16 v[10:13], v[210:213], v[184:187], v[10:13]
	v_mfma_f32_16x16x32_bf16 v[6:9], v[200:203], v[192:195], v[6:9]
	v_mfma_f32_16x16x32_bf16 v[2:5], v[210:213], v[192:195], v[2:5]
	s_add_i32 s70, s70, 2
	s_add_u32 s68, s68, 0x100
	s_addc_u32 s69, s69, 0
	s_add_u32 s50, s50, 0x100
	s_addc_u32 s51, s51, 0
	s_cmp_gt_u32 s70, 29
	s_barrier
	s_cbranch_scc0 .LBB0_354
	s_cmpk_gt_u32 s25, 0xff
	s_cbranch_scc1 .Ldsx0_354
	s_cmp_lg_u64 s[46:47], 0
	s_cbranch_scc1 .Ldsx0_354
	s_barrier
; __device__ __forceinline__ unsigned cvt_pk_bf16(float lo, float hi) { unsigned r; asm("v_cvt_pk_bf16_f32 %0, %1, %2" : "=v"(r) : "v"(lo), "v"(hi)); return r; }
; #define PG8_WAIT_V(n) asm volatile("s_waitcnt vmcnt(" #n ")" ::: "memory")
; #define PG8_BAR __builtin_amdgcn_s_barrier()
;     __device__ __forceinline__ void operator()(const f32x4 (&acc)[2][2][4][2], const Unit& u, int wr, int wc, int fr, int fq) const {
;         const int row0 = u.pm * BM + wr * 64 + fr, col0 = u.pn * BM + wc * 32 + 8 * fq;
; #pragma unroll
;         for (int ai = 0; ai < 2; ++ai)
; #pragma unroll
;             for (int m = 0; m < 4; ++m) { bf16_t* rowp = O + (size_t)(row0 + ai * HALF + m * 16) * ldc + col0;
; #pragma unroll
;                 for (int bj = 0; bj < 2; ++bj) { f32x4 v0 = acc[ai][bj][m][0], v1 = acc[ai][bj][m][1];
;                     if (ACT == 1) {
; #pragma unroll
;                         for (int j = 0; j < 4; ++j) { float a = fmaxf(v0[j], 0.f), b = fmaxf(v1[j], 0.f); v0[j] = a * a; v1[j] = b * b; } }
;                     u32x4 w; w.x = cvt_pk_bf16(v0[0], v0[1]); w.y = cvt_pk_bf16(v0[2], v0[3]); w.z = cvt_pk_bf16(v1[0], v1[1]); w.w = cvt_pk_bf16(v1[2], v1[3]);
;                     if (ACT == 1) __builtin_nontemporal_store(w, (u32x4*)(rowp + bj * HALF));
;                     else *(u32x4*)(rowp + bj * HALF) = w; } }
; template <class Epi, class Sched>
; __device__ __forceinline__ void gemm_phase(LAS unsigned char* lds, const Gemm g, const Sched& S, const Epi& E) {
;     ...
;         E(acc, cur, wr, wc, fr, fq);
;         if (!has_next) break;
; #pragma unroll
;         for (int a = 0; a < 2; ++a)
; #pragma unroll
;             for (int b = 0; b < 2; ++b)
; #pragma unroll
;                 for (int m = 0; m < 4; ++m)
; #pragma unroll
;                     for (int n = 0; n < 2; ++n) acc[a][b][m][n] = (f32x4){0.f, 0.f, 0.f, 0.f};
;         cur = nxt; cA = nA; cB = nB; ++ui;
;     }
;     PG8_WAIT_V(0);
;     if (wr == 0) PG8_BAR;
;     PG8_BAR;
.Ldsx0_354:
	s_load_dwordx2 s[50:51], s[0:1], 0xc0
	v_lshl_add_u32 v150, s28, 8, v144
	v_lshl_or_b32 v142, s40, 8, v146
	v_ashrrev_i32_e32 v143, 31, v142
	v_cvt_pk_bf16_f32 v70, v70, v71
	s_waitcnt lgkmcnt(0)
	v_mov_b64_e32 v[140:141], s[50:51]
	v_cvt_pk_bf16_f32 v71, v72, v73
	v_cvt_pk_bf16_f32 v72, v66, v67
	v_add_u32_e32 v66, 0x80, v150
	v_mad_i64_i32 v[148:149], s[50:51], v150, s17, v[140:141]
	v_lshlrev_b64 v[142:143], 1, v[142:143]
	v_cvt_pk_bf16_f32 v114, v114, v115
	v_cvt_pk_bf16_f32 v115, v116, v117
	v_cvt_pk_bf16_f32 v116, v106, v107
	v_or_b32_e32 v106, 16, v150
	v_mad_i64_i32 v[66:67], s[50:51], v66, s17, v[140:141]
	v_cvt_pk_bf16_f32 v50, v50, v51
	v_cvt_pk_bf16_f32 v51, v52, v53
	v_cvt_pk_bf16_f32 v52, v42, v43
	v_add_u32_e32 v42, 0x90, v150
	v_lshl_add_u64 v[148:149], v[148:149], 0, v[142:143]
	v_mad_i64_i32 v[106:107], s[50:51], v106, s17, v[140:141]
	v_cvt_pk_bf16_f32 v98, v98, v99
	v_cvt_pk_bf16_f32 v99, v100, v101
	v_cvt_pk_bf16_f32 v100, v90, v91
	v_or_b32_e32 v90, 32, v150
	v_lshl_add_u64 v[66:67], v[66:67], 0, v[142:143]
	v_mad_i64_i32 v[42:43], s[50:51], v42, s17, v[140:141]
	v_cvt_pk_bf16_f32 v34, v34, v35
	v_cvt_pk_bf16_f32 v35, v36, v37
	v_cvt_pk_bf16_f32 v36, v26, v27
	v_add_u32_e32 v26, 0xa0, v150
	v_cvt_pk_bf16_f32 v117, v108, v109
	global_store_dwordx4 v[148:149], v[114:117], off offset:256
	v_mad_i64_i32 v[90:91], s[50:51], v90, s17, v[140:141]
	s_nop 0
	v_lshl_add_u64 v[114:115], v[106:107], 0, v[142:143]
	v_cvt_pk_bf16_f32 v82, v82, v83
	v_cvt_pk_bf16_f32 v83, v84, v85
	v_cvt_pk_bf16_f32 v84, v74, v75
	v_or_b32_e32 v74, 48, v150
	v_cvt_pk_bf16_f32 v53, v44, v45
	global_store_dwordx4 v[66:67], v[50:53], off offset:256
	v_mad_i64_i32 v[26:27], s[50:51], v26, s17, v[140:141]
	s_nop 0
	v_lshl_add_u64 v[50:51], v[42:43], 0, v[142:143]
	v_cvt_pk_bf16_f32 v18, v18, v19
	v_cvt_pk_bf16_f32 v19, v20, v21
	v_cvt_pk_bf16_f32 v20, v10, v11
	v_add_u32_e32 v10, 0xb0, v150
	v_cvt_pk_bf16_f32 v101, v92, v93
	global_store_dwordx4 v[114:115], v[98:101], off offset:256
	v_mad_i64_i32 v[74:75], s[50:51], v74, s17, v[140:141]
	s_nop 0
	v_lshl_add_u64 v[98:99], v[90:91], 0, v[142:143]
	v_cvt_pk_bf16_f32 v37, v28, v29
	global_store_dwordx4 v[50:51], v[34:37], off offset:256
	v_mad_i64_i32 v[10:11], s[50:51], v10, s17, v[140:141]
	s_nop 0
	v_lshl_add_u64 v[34:35], v[26:27], 0, v[142:143]
	v_cvt_pk_bf16_f32 v85, v76, v77
	global_store_dwordx4 v[98:99], v[82:85], off offset:256
	v_cvt_pk_bf16_f32 v21, v12, v13
	global_store_dwordx4 v[34:35], v[18:21], off offset:256
	s_and_b64 vcc, exec, s[46:47]
	v_lshl_add_u64 v[82:83], v[74:75], 0, v[142:143]
	v_lshl_add_u64 v[18:19], v[10:11], 0, v[142:143]
	s_mov_b32 s40, s42
	s_mov_b32 s28, s8
	s_mov_b32 s43, s42
	s_mov_b32 s46, s8
	s_mov_b64 s[50:51], s[48:49]
	s_mov_b64 s[52:53], s[44:45]
	v_cvt_pk_bf16_f32 v126, v126, v127
	v_cvt_pk_bf16_f32 v127, v128, v129
	v_cvt_pk_bf16_f32 v128, v122, v123
	v_cvt_pk_bf16_f32 v129, v124, v125
	global_store_dwordx4 v[148:149], v[126:129], off
	v_cvt_pk_bf16_f32 v106, v118, v119
	v_cvt_pk_bf16_f32 v107, v120, v121
	v_cvt_pk_bf16_f32 v108, v110, v111
	v_cvt_pk_bf16_f32 v109, v112, v113
	global_store_dwordx4 v[114:115], v[106:109], off
	v_cvt_pk_bf16_f32 v90, v102, v103
	v_cvt_pk_bf16_f32 v91, v104, v105
	v_cvt_pk_bf16_f32 v92, v94, v95
	v_cvt_pk_bf16_f32 v93, v96, v97
	global_store_dwordx4 v[98:99], v[90:93], off
	v_cvt_pk_bf16_f32 v74, v86, v87
	v_cvt_pk_bf16_f32 v75, v88, v89
	v_cvt_pk_bf16_f32 v76, v78, v79
	v_cvt_pk_bf16_f32 v77, v80, v81
	global_store_dwordx4 v[82:83], v[74:77], off
	v_cvt_pk_bf16_f32 v73, v68, v69
	global_store_dwordx4 v[82:83], v[70:73], off offset:256
	v_cvt_pk_bf16_f32 v62, v62, v63
	v_cvt_pk_bf16_f32 v63, v64, v65
	v_cvt_pk_bf16_f32 v64, v58, v59
	v_cvt_pk_bf16_f32 v65, v60, v61
	global_store_dwordx4 v[66:67], v[62:65], off
	v_cvt_pk_bf16_f32 v42, v54, v55
	v_cvt_pk_bf16_f32 v43, v56, v57
	v_cvt_pk_bf16_f32 v44, v46, v47
	v_cvt_pk_bf16_f32 v45, v48, v49
	global_store_dwordx4 v[50:51], v[42:45], off
	v_cvt_pk_bf16_f32 v26, v38, v39
	v_cvt_pk_bf16_f32 v27, v40, v41
	v_cvt_pk_bf16_f32 v28, v30, v31
	v_cvt_pk_bf16_f32 v29, v32, v33
	global_store_dwordx4 v[34:35], v[26:29], off
	v_cvt_pk_bf16_f32 v10, v22, v23
	v_cvt_pk_bf16_f32 v11, v24, v25
	v_cvt_pk_bf16_f32 v12, v14, v15
	v_cvt_pk_bf16_f32 v13, v16, v17
	global_store_dwordx4 v[18:19], v[10:13], off
	v_cvt_pk_bf16_f32 v6, v6, v7
	v_cvt_pk_bf16_f32 v7, v8, v9
	v_cvt_pk_bf16_f32 v8, v2, v3
	v_cvt_pk_bf16_f32 v9, v4, v5
	global_store_dwordx4 v[18:19], v[6:9], off offset:256
	s_cbranch_vccz .LBB0_346
	s_waitcnt vmcnt(0)
	s_cmpk_gt_u32 s25, 0xff
	s_cbranch_scc1 .LBB0_358
	s_barrier
